# post3 row loop: d_scale and sub-LN weight vectors cached in registers (two fewer dependent round trips per row)
# baseline (speedup 1.0000x reference)
; #define TIDX ((int)((wave_s << 6) | lane_id_v()))
; __device__ __forceinline__ void phase_post3(const Params& p, int layer, float lambda_init, const int wave_s) {
;   int t_ = TIDX; asm volatile("" : "+v"(t_)); const int lane = t_ & 63, wave = __builtin_amdgcn_readfirstlane(t_ >> 6), gw = blockIdx.x * 8 + wave, NGW = gridDim.x * 8; (void)wave;
;   const bf16_t* P = (const bf16_t*)(p.ws + WS_P); const float* OA = (const float*)(p.ws + WS_OA); bf16_t* Y = (bf16_t*)(p.ws + WS_HY);
;   const float* lp = p.a_lambda + layer * 256; const float* sub = p.a_subln + layer * 128; const float* dsc = p.d_scale + layer * 512;
;   const float lam = __expf(wave_sum(lp[lane] * lp[64 + lane])) - __expf(wave_sum(lp[128 + lane] * lp[192 + lane])) + lambda_init;
;   const float post = 1.f - lambda_init;
;   const int h = lane >> 4, a = lane & 15;
;   const bool metasplit = (layer != DEPTH - 1);
;   const float* PART = (const float*)(p.ws + WS_PART);
;   for (int r = gw; r < LROWS; r += NGW) {
.LBB0_824:
	s_or_b64 exec, exec, s[0:1]
	s_waitcnt lgkmcnt(0)
	s_barrier
	v_mbcnt_lo_u32_b32 v0, -1, 0
	v_mbcnt_hi_u32_b32 v0, -1, v0
	v_readlane_b32 s2, v255, 7
	v_or_b32_e32 v0, s61, v0
	v_readlane_b32 s3, v255, 8
	v_readfirstlane_b32 s0, v0
	s_ashr_i32 s0, s0, 6
	s_lshl_b32 s4, s2, 8
	v_readlane_b32 s36, v254, 27
	s_add_i32 s22, s0, s75
	s_lshl_b64 s[2:3], s[4:5], 2
	v_readlane_b32 s40, v254, 31
	v_and_b32_e32 v1, 63, v0
	v_readlane_b32 s41, v254, 32
	s_add_u32 s2, s40, s2
	s_addc_u32 s3, s41, s3
	v_lshlrev_b32_e32 v2, 2, v1
	global_load_dword v3, v2, s[2:3]
	global_load_dword v4, v2, s[2:3] offset:256
	global_load_dword v5, v2, s[2:3] offset:512
	s_nop 0
	global_load_dword v2, v2, s[2:3] offset:768
	v_cmp_lt_i32_e32 vcc, v198, v197
	s_cmpk_gt_i32 s22, 0x400f
	v_readlane_b32 s37, v254, 28
	v_cndmask_b32_e32 v6, v196, v198, vcc
	v_lshlrev_b32_e32 v114, 2, v6
	v_cmp_lt_i32_e32 vcc, v199, v197
	v_readlane_b32 s38, v254, 29
	v_readlane_b32 s39, v254, 30
	v_cndmask_b32_e32 v8, v196, v199, vcc
	v_lshlrev_b32_e32 v115, 2, v8
	v_cmp_lt_i32_e32 vcc, v200, v197
	v_readlane_b32 s42, v254, 33
	v_readlane_b32 s43, v254, 34
	v_readlane_b32 s44, v254, 35
	v_readlane_b32 s45, v254, 36
	v_readlane_b32 s46, v254, 37
	v_readlane_b32 s47, v254, 38
	v_readlane_b32 s48, v254, 39
	v_readlane_b32 s49, v254, 40
	v_readlane_b32 s50, v254, 41
	v_readlane_b32 s51, v254, 42
	s_waitcnt vmcnt(2)
	v_mul_f32_e32 v6, v3, v4
	ds_bpermute_b32 v6, v114, v6
	s_waitcnt vmcnt(0)
	v_mul_f32_e32 v7, v5, v2
	ds_bpermute_b32 v7, v114, v7
	s_waitcnt lgkmcnt(1)
	v_fmac_f32_e32 v6, v3, v4
	v_cndmask_b32_e32 v4, v196, v200, vcc
	s_waitcnt lgkmcnt(0)
	v_fmac_f32_e32 v7, v5, v2
	ds_bpermute_b32 v2, v115, v6
	ds_bpermute_b32 v3, v115, v7
	v_lshlrev_b32_e32 v116, 2, v4
	v_cmp_lt_i32_e32 vcc, v201, v197
	s_waitcnt lgkmcnt(1)
	v_add_f32_e32 v2, v6, v2
	s_waitcnt lgkmcnt(0)
	v_add_f32_e32 v3, v7, v3
	ds_bpermute_b32 v4, v116, v2
	ds_bpermute_b32 v5, v116, v3
	v_cndmask_b32_e32 v6, v196, v201, vcc
	v_lshlrev_b32_e32 v117, 2, v6
	v_cmp_lt_i32_e32 vcc, v202, v197
	s_waitcnt lgkmcnt(1)
	v_add_f32_e32 v2, v2, v4
	s_waitcnt lgkmcnt(0)
	v_add_f32_e32 v3, v3, v5
	ds_bpermute_b32 v4, v117, v2
	ds_bpermute_b32 v5, v117, v3
	v_cndmask_b32_e32 v6, v196, v202, vcc
	v_lshlrev_b32_e32 v6, 2, v6
	v_cmp_lt_i32_e32 vcc, v203, v197
	s_waitcnt lgkmcnt(1)
	v_add_f32_e32 v2, v2, v4
	s_waitcnt lgkmcnt(0)
	v_add_f32_e32 v4, v3, v5
	ds_bpermute_b32 v3, v6, v2
	ds_bpermute_b32 v5, v6, v4
	v_cndmask_b32_e32 v6, v196, v203, vcc
	v_lshlrev_b32_e32 v6, 2, v6
	s_waitcnt lgkmcnt(1)
	v_add_f32_e32 v3, v2, v3
	s_waitcnt lgkmcnt(0)
	v_add_f32_e32 v2, v4, v5
	ds_bpermute_b32 v5, v6, v3
	ds_bpermute_b32 v4, v6, v2
	s_cbranch_scc1 .LBB0_831
	s_waitcnt lgkmcnt(1)
	v_add_f32_e32 v3, v3, v5
	s_waitcnt lgkmcnt(0)
	v_add_f32_e32 v2, v2, v4
	v_mul_f32_e32 v3, 0x3fb8aa3b, v3
	v_mul_f32_e32 v2, 0x3fb8aa3b, v2
	v_exp_f32_e32 v3, v3
	v_exp_f32_e32 v2, v2
	v_mov_b32_e32 v4, 0x3eb60549
	v_cndmask_b32_e64 v4, v4, v250, s[68:69]
	v_sub_f32_e32 v64, 1.0, v4
	v_sub_f32_e32 v2, v3, v2
	v_lshrrev_b32_e32 v3, 4, v1
	v_add_f32_e32 v66, v4, v2
	v_readlane_b32 s6, v255, 7
	v_mul_u32_u24_e32 v4, 0x8400, v3
	v_readlane_b32 s18, v252, 51
	s_lshl_b32 s4, s6, 9
	v_lshlrev_b32_e32 v4, 2, v4
	v_mov_b32_e32 v5, v169
	v_readlane_b32 s19, v252, 52
	s_lshl_b64 s[2:3], s[4:5], 2
	v_readlane_b32 s24, v254, 11
	v_lshl_add_u64 v[4:5], s[18:19], 0, v[4:5]
	s_mov_b64 s[8:9], 0x84000
	v_readlane_b32 s25, v254, 12
	s_add_u32 s2, s24, s2
	v_lshl_add_u64 v[68:69], v[4:5], 0, s[8:9]
	v_lshlrev_b32_e32 v4, 4, v0
	v_readlane_b32 s7, v255, 8
	s_addc_u32 s3, s25, s3
	s_lshl_b32 s4, s6, 7
	v_readlane_b32 s36, v254, 27
	v_and_b32_e32 v4, 0x300, v4
	s_lshl_b64 s[6:7], s[4:5], 2
	v_readlane_b32 s42, v254, 33
	v_lshlrev_b32_e32 v2, 3, v0
	v_mul_u32_u24_e32 v4, 0x84, v4
	v_readlane_b32 s43, v254, 34
	s_add_u32 s6, s42, s6
	v_and_b32_e32 v2, 0x78, v2
	v_lshlrev_b32_e32 v4, 2, v4
	v_mov_b32_e32 v5, v169
	s_addc_u32 s7, s43, s7
	v_lshlrev_b32_e32 v168, 8, v3
	v_lshl_add_u64 v[4:5], s[18:19], 0, v[4:5]
	s_mov_b64 s[8:9], 0x94800
	v_mul_u32_u24_e32 v3, 0x4200, v3
	v_lshlrev_b32_e32 v6, 2, v2
	v_mov_b32_e32 v7, v169
	s_mulk_i32 s0, 0x84
	s_mul_i32 s1, s60, 0x420
	s_ashr_i32 s23, s22, 31
	v_lshl_add_u64 v[70:71], v[4:5], 0, s[8:9]
	v_lshlrev_b32_e32 v4, 2, v3
	v_mov_b32_e32 v5, v169
	v_lshl_add_u64 v[76:77], s[6:7], 0, v[6:7]
	v_lshlrev_b32_e32 v6, 5, v1
	s_add_i32 s28, s1, s0
	s_lshl_b64 s[34:35], s[22:23], 12
	v_lshl_add_u64 v[72:73], s[18:19], 0, v[4:5]
	v_lshlrev_b32_e32 v4, 3, v1
	v_lshl_add_u64 v[78:79], s[2:3], 0, v[6:7]
	v_lshlrev_b32_e32 v6, 4, v1
	s_add_u32 s0, s34, 0x1a080000
	v_and_b32_e32 v1, 48, v0
	v_and_b32_e32 v0, 15, v0
	s_addc_u32 s1, s35, 0
	v_lshlrev_b32_e32 v1, 6, v1
	v_lshlrev_b32_e32 v3, 5, v0
	v_or3_b32 v82, s0, v1, v3
	s_add_u32 s0, s34, 0x4320400
	s_mov_b64 s[8:9], 0x42000
	v_readlane_b32 s2, v252, 49
	v_mov_b32_e32 v83, s1
	s_addc_u32 s1, s35, 0
	v_lshlrev_b32_e32 v0, 4, v0
	v_readlane_b32 s37, v254, 28
	v_lshl_add_u64 v[74:75], v[72:73], 0, s[8:9]
	v_readlane_b32 s3, v252, 50
	v_or3_b32 v84, s0, v168, v0
	v_mov_b32_e32 v85, s1
	v_mad_i64_i32 v[86:87], s[0:1], s22, v207, v[168:169]
	v_readlane_b32 s8, v253, 53
	v_mov_b32_e32 v65, v64
	v_mov_b32_e32 v67, v66
	v_lshl_add_u64 v[80:81], s[2:3], 0, v[6:7]
	s_mul_hi_i32 s37, s22, 0x2e00
	s_mul_i32 s36, s22, 0x2e00
	v_or_b32_e32 v86, v86, v0
	v_lshlrev_b32_e32 v88, 2, v2
	v_lshlrev_b32_e32 v168, 1, v4
	v_readlane_b32 s9, v253, 54
	s_mov_b32 s4, 0x8420000
	s_mov_b32 s12, 0xc2fc0000
	s_mov_b64 s[18:19], 0x2100
	v_readlane_b32 s26, v254, 13
	v_readlane_b32 s27, v254, 14
	v_readlane_b32 s38, v254, 29
	v_readlane_b32 s39, v254, 30
	v_readlane_b32 s40, v254, 31
	v_readlane_b32 s41, v254, 32
	v_readlane_b32 s44, v254, 35
	v_readlane_b32 s45, v254, 36
	v_readlane_b32 s46, v254, 37
	v_readlane_b32 s47, v254, 38
	v_readlane_b32 s48, v254, 39
	v_readlane_b32 s49, v254, 40
	v_readlane_b32 s50, v254, 41
	v_readlane_b32 s51, v254, 42
	global_load_dwordx4 v[126:129], v[78:79], off offset:16
	global_load_dwordx4 v[130:133], v[78:79], off
	global_load_dwordx4 v[134:137], v[76:77], off offset:16
	global_load_dwordx4 v[138:141], v[76:77], off
	s_waitcnt vmcnt(0)
	s_branch .LBB0_827
; __device__ __forceinline__ float silu(float g) { return g / (1.f + __expf(-g)); }
; __device__ __forceinline__ void unpack8(const u32x4 w, float* x) { x[0] = bflo(w.x); x[1] = bfhi(w.x); x[2] = bflo(w.y); x[3] = bfhi(w.y); x[4] = bflo(w.z); x[5] = bfhi(w.z); x[6] = bflo(w.w); x[7] = bfhi(w.w); }
; __device__ __forceinline__ u32x4 pack8(const float* x) { u32x4 w; w.x = pk2(x[0], x[1]); w.y = pk2(x[2], x[3]); w.z = pk2(x[4], x[5]); w.w = pk2(x[6], x[7]); return w; }
; __device__ __forceinline__ void phase_post3(const Params& p, int layer, float lambda_init, const int wave_s) {
;     ...
;     { float m[8], g[8]; unpack8(*(const u32x4*)(P + (size_t)r * INP + C_DU + lane * 8), m); unpack8(*(const u32x4*)(P + (size_t)r * INP + C_DG + lane * 8), g);
; #pragma unroll
;       for (int i = 0; i < 8; ++i) m[i] = m[i] * dsc[lane * 8 + i] * silu(g[i]);
;       *(u32x4*)(Y + (size_t)r * DM + 1536 + lane * 8) = pack8(m); }
.LBB0_826:
	s_add_u32 s0, s10, s0
	s_addc_u32 s1, s11, s1
	v_lshl_add_u64 v[0:1], s[0:1], 0, v[168:169]
	v_add_co_u32_e32 v0, vcc, 0x2000, v0
	s_add_i32 s22, s22, s80
	s_nop 0
	v_addc_co_u32_e32 v1, vcc, 0, v1, vcc
	global_load_dwordx4 v[6:9], v[0:1], off offset:1408
	global_load_dwordx4 v[2:5], v[0:1], off offset:2432
	v_lshl_add_u64 v[86:87], v[86:87], 0, s[8:9]
	s_waitcnt vmcnt(1)
	v_lshlrev_b32_e32 v18, 16, v6
	s_waitcnt vmcnt(0)
	v_lshlrev_b32_e32 v22, 16, v2
	v_and_b32_e32 v24, 0xffff0000, v2
	v_mul_f32_e32 v0, 0xbfb8aa3b, v22
	v_and_b32_e32 v10, 0xffff0000, v6
	v_exp_f32_e32 v6, v0
	v_mul_f32_e32 v0, 0xbfb8aa3b, v24
	v_lshlrev_b32_e32 v13, 16, v3
	v_and_b32_e32 v23, 0xffff0000, v3
	v_exp_f32_e32 v12, v0
	v_mov_b32_e32 v0, v126
	v_mov_b32_e32 v1, v127
	v_mov_b32_e32 v2, v128
	v_mov_b32_e32 v3, v129
	v_mov_b32_e32 v14, v130
	v_mov_b32_e32 v15, v131
	v_mov_b32_e32 v16, v132
	v_mov_b32_e32 v17, v133
	v_lshlrev_b32_e32 v19, 16, v7
	v_and_b32_e32 v11, 0xffff0000, v7
	v_mul_f32_e32 v7, 0xbfb8aa3b, v13
	v_exp_f32_e32 v7, v7

; __device__ __forceinline__ float silu(float g) { return g / (1.f + __expf(-g)); }
; __device__ __forceinline__ float sum16(float v) { v += __shfl_xor(v, 1); v += __shfl_xor(v, 2); v += __shfl_xor(v, 4); v += __shfl_xor(v, 8); return v; }
; __device__ __forceinline__ void unpack8(const u32x4 w, float* x) { x[0] = bflo(w.x); x[1] = bfhi(w.x); x[2] = bflo(w.y); x[3] = bfhi(w.y); x[4] = bflo(w.z); x[5] = bfhi(w.z); x[6] = bflo(w.w); x[7] = bfhi(w.w); }
; __device__ __forceinline__ u32x4 pack8(const float* x) { u32x4 w; w.x = pk2(x[0], x[1]); w.y = pk2(x[2], x[3]); w.z = pk2(x[4], x[5]); w.w = pk2(x[6], x[7]); return w; }
; __device__ __forceinline__ void phase_post3(const Params& p, int layer, float lambda_init, const int wave_s) {
;     ...
;     { const f32x4* o1 = (const f32x4*)(OA + (size_t)r * 1024 + (2 * h) * 128 + a * 8); const f32x4* o2 = (const f32x4*)(OA + (size_t)r * 1024 + (2 * h + 1) * 128 + a * 8);
;       const f32x4 u0 = o1[0], u1 = o1[1], v0 = o2[0], v1 = o2[1];
;       float x[8] = {u0.x - lam * v0.x, u0.y - lam * v0.y, u0.z - lam * v0.z, u0.w - lam * v0.w, u1.x - lam * v1.x, u1.y - lam * v1.y, u1.z - lam * v1.z, u1.w - lam * v1.w};
;       float ss = 0.f;
; #pragma unroll
;       for (int i = 0; i < 8; ++i) ss += x[i] * x[i];
;       const float rs = rsqrtf(sum16(ss) * (1.f / 128.f) + EPS);
;       float g[8]; unpack8(*(const u32x4*)(P + (size_t)r * INP + C_AG + h * 128 + a * 8), g);
;     ...
;     { float m[8], g[8]; unpack8(*(const u32x4*)(P + (size_t)r * INP + C_DU + lane * 8), m); unpack8(*(const u32x4*)(P + (size_t)r * INP + C_DG + lane * 8), g);
; #pragma unroll
;       for (int i = 0; i < 8; ++i) m[i] = m[i] * dsc[lane * 8 + i] * silu(g[i]);
;       *(u32x4*)(Y + (size_t)r * DM + 1536 + lane * 8) = pack8(m); }
	v_mov_b32_e32 v20, v14
	v_pk_add_f32 v[6:7], v[6:7], 1.0 op_sel_hi:[1,0]
	v_mov_b32_e32 v21, v16
	v_div_scale_f32 v14, s[0:1], v7, v7, v13
	v_rcp_f32_e32 v16, v14
	v_pk_mul_f32 v[18:19], v[20:21], v[18:19]
	v_fma_f32 v20, -v14, v16, 1.0
	v_fmac_f32_e32 v16, v20, v16
	v_div_scale_f32 v20, vcc, v13, v7, v13
	v_mul_f32_e32 v21, v20, v16
	v_fma_f32 v25, -v14, v21, v20
	v_fmac_f32_e32 v21, v25, v16
	v_fma_f32 v14, -v14, v21, v20
	v_div_fmas_f32 v14, v14, v16, v21
	v_div_fixup_f32 v7, v14, v7, v13
	v_div_scale_f32 v13, s[0:1], v6, v6, v22
	v_rcp_f32_e32 v14, v13
	s_nop 0
	v_fma_f32 v16, -v13, v14, 1.0
	v_fmac_f32_e32 v14, v16, v14
	v_div_scale_f32 v16, vcc, v22, v6, v22
	v_mul_f32_e32 v20, v16, v14
	v_fma_f32 v21, -v13, v20, v16
	v_fmac_f32_e32 v20, v21, v14
	v_fma_f32 v13, -v13, v20, v16
	v_div_fmas_f32 v13, v13, v14, v20
	v_div_fixup_f32 v6, v13, v6, v22
	v_mul_f32_e32 v13, 0xbfb8aa3b, v23
	v_exp_f32_e32 v13, v13
	v_mov_b32_e32 v16, v15
	v_pk_mul_f32 v[10:11], v[16:17], v[10:11]
	v_pk_mul_f32 v[6:7], v[18:19], v[6:7]
	v_pk_add_f32 v[12:13], v[12:13], 1.0 op_sel_hi:[1,0]
	v_lshlrev_b32_e32 v19, 16, v4
	v_div_scale_f32 v14, s[0:1], v13, v13, v23
	v_rcp_f32_e32 v15, v14
	v_and_b32_e32 v21, 0xffff0000, v4
	v_mul_f32_e32 v4, 0xbfb8aa3b, v19
	v_and_b32_e32 v20, 0xffff0000, v5
	v_fma_f32 v16, -v14, v15, 1.0
	v_fmac_f32_e32 v15, v16, v15
	v_div_scale_f32 v16, vcc, v23, v13, v23
	v_mul_f32_e32 v17, v16, v15
	v_fma_f32 v18, -v14, v17, v16
	v_fmac_f32_e32 v17, v18, v15
	v_fma_f32 v14, -v14, v17, v16
	v_div_fmas_f32 v14, v14, v15, v17
	v_div_fixup_f32 v13, v14, v13, v23
	v_div_scale_f32 v14, s[0:1], v12, v12, v24
	v_rcp_f32_e32 v15, v14
	s_nop 0
	v_fma_f32 v16, -v14, v15, 1.0
	v_fmac_f32_e32 v15, v16, v15
	v_div_scale_f32 v16, vcc, v24, v12, v24
	v_mul_f32_e32 v17, v16, v15
	v_fma_f32 v18, -v14, v17, v16
	v_fmac_f32_e32 v17, v18, v15
	v_fma_f32 v14, -v14, v17, v16
	v_lshlrev_b32_e32 v18, 16, v5
	v_div_fmas_f32 v14, v14, v15, v17
	v_mov_b32_e32 v16, v0
	v_mul_f32_e32 v0, 0xbfb8aa3b, v18
	v_div_fixup_f32 v12, v14, v12, v24
	v_exp_f32_e32 v14, v4
	v_exp_f32_e32 v15, v0
	v_mov_b32_e32 v17, v2
	v_pk_mul_f32 v[10:11], v[10:11], v[12:13]
	v_lshlrev_b32_e32 v13, 16, v9
	v_pk_add_f32 v[14:15], v[14:15], 1.0 op_sel_hi:[1,0]
	v_lshlrev_b32_e32 v12, 16, v8
	v_div_scale_f32 v0, s[0:1], v15, v15, v18
	v_rcp_f32_e32 v2, v0
	v_pk_mul_f32 v[12:13], v[16:17], v[12:13]
	v_and_b32_e32 v9, 0xffff0000, v9
	v_and_b32_e32 v8, 0xffff0000, v8
	v_fma_f32 v5, -v0, v2, 1.0
	v_fmac_f32_e32 v2, v5, v2
	v_div_scale_f32 v5, vcc, v18, v15, v18
	v_mul_f32_e32 v16, v5, v2
	v_fma_f32 v17, -v0, v16, v5
	v_fmac_f32_e32 v16, v17, v2
	v_fma_f32 v0, -v0, v16, v5
	v_div_fmas_f32 v0, v0, v2, v16
	v_div_fixup_f32 v15, v0, v15, v18
	v_div_scale_f32 v0, s[0:1], v14, v14, v19
	v_rcp_f32_e32 v2, v0
	v_mul_f32_e32 v4, 0xbfb8aa3b, v21
	v_exp_f32_e32 v4, v4
	v_fma_f32 v5, -v0, v2, 1.0
	v_fmac_f32_e32 v2, v5, v2
	v_div_scale_f32 v5, vcc, v19, v14, v19
	v_mul_f32_e32 v16, v5, v2
	v_fma_f32 v17, -v0, v16, v5
	v_fmac_f32_e32 v16, v17, v2
	v_fma_f32 v0, -v0, v16, v5
	v_div_fmas_f32 v0, v0, v2, v16
	v_mov_b32_e32 v2, v1
	v_div_fixup_f32 v14, v0, v14, v19
	v_pk_mul_f32 v[0:1], v[2:3], v[8:9]
	v_mul_f32_e32 v2, 0xbfb8aa3b, v20
	v_exp_f32_e32 v5, v2
	v_pk_mul_f32 v[12:13], v[12:13], v[14:15]
	v_pk_add_f32 v[2:3], v[4:5], 1.0 op_sel_hi:[1,0]
	s_nop 0
	v_div_scale_f32 v4, s[0:1], v3, v3, v20
	v_rcp_f32_e32 v5, v4
	s_nop 0
	v_fma_f32 v8, -v4, v5, 1.0
	v_fmac_f32_e32 v5, v8, v5
	v_div_scale_f32 v8, vcc, v20, v3, v20
	v_mul_f32_e32 v9, v8, v5
	v_fma_f32 v14, -v4, v9, v8
	v_fmac_f32_e32 v9, v14, v5
	v_fma_f32 v4, -v4, v9, v8
	v_div_fmas_f32 v4, v4, v5, v9
	v_div_fixup_f32 v3, v4, v3, v20
	v_div_scale_f32 v4, s[0:1], v2, v2, v21
	v_rcp_f32_e32 v5, v4
	s_mul_i32 s0, s76, 0x420
	s_add_i32 s28, s28, s0
	v_readlane_b32 s0, v253, 63
	v_fma_f32 v8, -v4, v5, 1.0
	v_fmac_f32_e32 v5, v8, v5
	v_div_scale_f32 v8, vcc, v21, v2, v21
	v_mul_f32_e32 v9, v8, v5
	v_fma_f32 v14, -v4, v9, v8
	v_fmac_f32_e32 v9, v14, v5
	v_fma_f32 v4, -v4, v9, v8
	v_div_fmas_f32 v4, v4, v5, v9
	v_div_fixup_f32 v2, v4, v2, v21
	v_pk_mul_f32 v[0:1], v[0:1], v[2:3]
	v_readlane_b32 s1, v254, 0
	v_bfe_u32 v2, v1, 16, 1
	v_bfe_u32 v3, v0, 16, 1
	s_add_u32 s34, s34, s0
	v_add3_u32 v0, v0, v3, s15
	v_add3_u32 v1, v1, v2, s15
	v_bfe_u32 v2, v6, 16, 1
	v_bfe_u32 v3, v7, 16, 1
	v_bfe_u32 v8, v12, 16, 1
	v_bfe_u32 v9, v13, 16, 1
	s_addc_u32 s35, s35, s1
	v_bfe_u32 v4, v11, 16, 1
	v_bfe_u32 v5, v10, 16, 1
	v_add3_u32 v9, v13, v9, s15
	v_add3_u32 v8, v12, v8, s15
	v_add3_u32 v3, v7, v3, s15
	v_add3_u32 v2, v6, v2, s15
	s_add_u32 s36, s36, s8
	v_add3_u32 v5, v10, v5, s15
	v_add3_u32 v4, v11, v4, s15
	v_lshrrev_b32_e32 v6, 16, v2
	v_lshrrev_b32_e32 v7, 16, v3
	v_lshrrev_b32_e32 v2, 16, v8
	v_lshrrev_b32_e32 v3, 16, v9
	s_addc_u32 s37, s37, s9
	v_and_or_b32 v3, v1, s14, v3
	v_and_or_b32 v2, v0, s14, v2
	v_and_or_b32 v1, v4, s14, v7
	v_and_or_b32 v0, v5, s14, v6
	v_lshl_add_u64 v[4:5], v[80:81], 0, s[38:39]
	v_lshl_add_u64 v[82:83], v[82:83], 0, s[0:1]
	v_lshl_add_u64 v[84:85], v[84:85], 0, s[0:1]
	s_cmpk_lt_i32 s22, 0x4010
	global_store_dwordx4 v[4:5], v[0:3], off offset:3072
	s_cbranch_scc0 .LBB0_831
.LBB0_827:
	s_cmp_gt_i32 s22, 15
	s_cselect_b64 s[0:1], -1, 0
	s_xor_b64 s[2:3], s[68:69], -1
	s_or_b64 s[0:1], s[2:3], s[0:1]
	s_mov_b64 s[6:7], -1
	s_and_b64 vcc, exec, s[0:1]
	v_lshl_add_u64 v[92:93], s[78:79], 0, v[86:87]
	v_lshl_add_u64 v[90:91], s[78:79], 0, v[84:85]
	s_cbranch_vccz .LBB0_829
	v_lshl_add_u64 v[4:5], s[78:79], 0, v[82:83]
	global_load_dwordx4 v[10:13], v[4:5], off offset:16
	global_load_dwordx4 v[0:3], v[4:5], off
	global_load_dwordx4 v[14:17], v[4:5], off offset:528
	global_load_dwordx4 v[22:25], v[4:5], off offset:512
	v_add_co_u32_e32 v4, vcc, s4, v92
	s_ashr_i32 s23, s22, 31
	s_nop 0
	v_addc_co_u32_e32 v5, vcc, 0, v93, vcc
	global_load_dwordx4 v[6:9], v[4:5], off offset:3072
	s_lshl_b64 s[38:39], s[22:23], 12
	s_mul_hi_i32 s1, s22, 0x2e00
	s_mul_i32 s0, s22, 0x2e00
	s_mov_b64 s[6:7], 0
	s_waitcnt vmcnt(3)
	v_mov_b32_e32 v18, v0
	v_mov_b32_e32 v19, v2
	s_waitcnt vmcnt(1)
	v_mov_b32_e32 v4, v22
	v_mov_b32_e32 v5, v24
	v_mov_b32_e32 v24, v23
	v_mov_b32_e32 v2, v1
	v_pk_fma_f32 v[20:21], v[66:67], v[4:5], v[18:19] neg_lo:[1,0,0] neg_hi:[1,0,0]
	v_pk_fma_f32 v[18:19], v[66:67], v[24:25], v[2:3] neg_lo:[1,0,0] neg_hi:[1,0,0]
	v_mov_b32_e32 v1, v21
	v_mov_b32_e32 v0, v19
	s_waitcnt vmcnt(0)
	v_lshlrev_b32_e32 v30, 16, v6
	v_pk_mul_f32 v[22:23], v[0:1], v[0:1]
	v_and_b32_e32 v32, 0xffff0000, v6
	v_mul_f32_e32 v0, 0xbfb8aa3b, v30
	v_exp_f32_e32 v26, v0
	v_mul_f32_e32 v0, 0xbfb8aa3b, v32
	v_lshlrev_b32_e32 v29, 16, v7
	v_and_b32_e32 v31, 0xffff0000, v7
	v_exp_f32_e32 v28, v0
	v_mov_b32_e32 v0, v134
	v_mov_b32_e32 v1, v135
	v_mov_b32_e32 v2, v136
	v_mov_b32_e32 v3, v137
	v_mov_b32_e32 v4, v138
	v_mov_b32_e32 v5, v139
	v_mov_b32_e32 v6, v140
	v_mov_b32_e32 v7, v141

; __device__ __forceinline__ float silu(float g) { return g / (1.f + __expf(-g)); }
; __device__ __forceinline__ float sum16(float v) { v += __shfl_xor(v, 1); v += __shfl_xor(v, 2); v += __shfl_xor(v, 4); v += __shfl_xor(v, 8); return v; }
; __device__ __forceinline__ void unpack8(const u32x4 w, float* x) { x[0] = bflo(w.x); x[1] = bfhi(w.x); x[2] = bflo(w.y); x[3] = bfhi(w.y); x[4] = bflo(w.z); x[5] = bfhi(w.z); x[6] = bflo(w.w); x[7] = bfhi(w.w); }
; __device__ __forceinline__ u32x4 pack8(const float* x) { u32x4 w; w.x = pk2(x[0], x[1]); w.y = pk2(x[2], x[3]); w.z = pk2(x[4], x[5]); w.w = pk2(x[6], x[7]); return w; }
; __device__ __forceinline__ void phase_post3(const Params& p, int layer, float lambda_init, const int wave_s) {
;     ...
;     { const f32x4* o1 = (const f32x4*)(OA + (size_t)r * 1024 + (2 * h) * 128 + a * 8); const f32x4* o2 = (const f32x4*)(OA + (size_t)r * 1024 + (2 * h + 1) * 128 + a * 8);
;       const f32x4 u0 = o1[0], u1 = o1[1], v0 = o2[0], v1 = o2[1];
;       float x[8] = {u0.x - lam * v0.x, u0.y - lam * v0.y, u0.z - lam * v0.z, u0.w - lam * v0.w, u1.x - lam * v1.x, u1.y - lam * v1.y, u1.z - lam * v1.z, u1.w - lam * v1.w};
;       float ss = 0.f;
; #pragma unroll
;       for (int i = 0; i < 8; ++i) ss += x[i] * x[i];
;       const float rs = rsqrtf(sum16(ss) * (1.f / 128.f) + EPS);
;       float g[8]; unpack8(*(const u32x4*)(P + (size_t)r * INP + C_AG + h * 128 + a * 8), g);
; #pragma unroll
;       for (int i = 0; i < 8; ++i) x[i] = x[i] * rs * sub[a * 8 + i] * post * silu(g[i]);
;       *(u32x4*)(Y + (size_t)r * DM + h * 128 + a * 8) = pack8(x); }
	v_mov_b32_e32 v24, v4
	v_mul_f32_e32 v4, 0xbfb8aa3b, v29
	v_exp_f32_e32 v27, v4
	v_mov_b32_e32 v25, v6
	v_pk_add_f32 v[26:27], v[26:27], 1.0 op_sel_hi:[1,0]
	s_nop 0
	v_div_scale_f32 v4, s[2:3], v27, v27, v29
	v_rcp_f32_e32 v6, v4
	s_nop 0
	v_fma_f32 v33, -v4, v6, 1.0
	v_fmac_f32_e32 v6, v33, v6
	v_div_scale_f32 v33, vcc, v29, v27, v29
	v_mul_f32_e32 v34, v33, v6
	v_fma_f32 v35, -v4, v34, v33
	v_fmac_f32_e32 v34, v35, v6
	v_fma_f32 v4, -v4, v34, v33
	v_div_fmas_f32 v4, v4, v6, v34
	v_div_fixup_f32 v27, v4, v27, v29
	v_div_scale_f32 v4, s[2:3], v26, v26, v30
	v_rcp_f32_e32 v6, v4
	s_nop 0
	v_fma_f32 v29, -v4, v6, 1.0
	v_fmac_f32_e32 v6, v29, v6
	v_div_scale_f32 v29, vcc, v30, v26, v30
	v_mul_f32_e32 v33, v29, v6
	v_fma_f32 v34, -v4, v33, v29
	v_fmac_f32_e32 v33, v34, v6
	v_fma_f32 v4, -v4, v33, v29
	v_div_fmas_f32 v4, v4, v6, v33
	v_div_fixup_f32 v26, v4, v26, v30
	v_mul_f32_e32 v4, 0xbfb8aa3b, v31
	v_exp_f32_e32 v29, v4
	v_mov_b32_e32 v6, v5
	v_pk_add_f32 v[4:5], v[28:29], 1.0 op_sel_hi:[1,0]
	s_nop 0
	v_div_scale_f32 v28, s[2:3], v5, v5, v31
	v_rcp_f32_e32 v29, v28
	s_nop 0
	v_fma_f32 v30, -v28, v29, 1.0
	v_fmac_f32_e32 v29, v30, v29
	v_div_scale_f32 v30, vcc, v31, v5, v31
	v_mul_f32_e32 v33, v30, v29
	v_fma_f32 v34, -v28, v33, v30
	v_fmac_f32_e32 v33, v34, v29
	v_fma_f32 v28, -v28, v33, v30
	v_div_fmas_f32 v28, v28, v29, v33
	v_div_fixup_f32 v5, v28, v5, v31
	v_div_scale_f32 v28, s[2:3], v4, v4, v32
	v_rcp_f32_e32 v29, v28
	s_nop 0
	v_fma_f32 v30, -v28, v29, 1.0
	v_fmac_f32_e32 v29, v30, v29
	v_div_scale_f32 v30, vcc, v32, v4, v32
	v_mul_f32_e32 v31, v30, v29
	v_fma_f32 v33, -v28, v31, v30
	v_fmac_f32_e32 v31, v33, v29
	v_fma_f32 v28, -v28, v31, v30
	v_div_fmas_f32 v28, v28, v29, v31
	v_div_fixup_f32 v4, v28, v4, v32
	v_mov_b32_e32 v28, v14
	v_mov_b32_e32 v29, v16
	v_mov_b32_e32 v30, v10
	v_mov_b32_e32 v31, v12
	v_mov_b32_e32 v16, v15
	v_mov_b32_e32 v12, v11
	v_and_b32_e32 v32, 0xffff0000, v8
	v_pk_fma_f32 v[28:29], v[66:67], v[28:29], v[30:31] neg_lo:[1,0,0] neg_hi:[1,0,0]
	v_pk_fma_f32 v[10:11], v[66:67], v[16:17], v[12:13] neg_lo:[1,0,0] neg_hi:[1,0,0]
	v_lshlrev_b32_e32 v17, 16, v9
	v_lshlrev_b32_e32 v30, 16, v8
	v_and_b32_e32 v31, 0xffff0000, v9
	v_mul_f32_e32 v9, 0xbfb8aa3b, v32
	v_mul_f32_e32 v8, 0xbfb8aa3b, v30
	v_exp_f32_e32 v16, v9
	v_mul_f32_e32 v9, 0xbfb8aa3b, v17
	v_exp_f32_e32 v8, v8
	v_exp_f32_e32 v9, v9
	v_mov_b32_e32 v12, v10
	v_mov_b32_e32 v13, v28
	v_pk_mul_f32 v[12:13], v[12:13], v[12:13]
	v_pk_add_f32 v[8:9], v[8:9], 1.0 op_sel_hi:[1,0]
	v_mov_b32_e32 v14, v11
	v_div_scale_f32 v33, s[2:3], v9, v9, v17
	v_rcp_f32_e32 v34, v33
	v_mov_b32_e32 v15, v29
	v_pk_mul_f32 v[14:15], v[14:15], v[14:15]
	v_fma_f32 v35, -v33, v34, 1.0
	v_fmac_f32_e32 v34, v35, v34
	v_div_scale_f32 v35, vcc, v17, v9, v17
	v_mul_f32_e32 v36, v35, v34
	v_fma_f32 v37, -v33, v36, v35
	v_fmac_f32_e32 v36, v37, v34
	v_fma_f32 v33, -v33, v36, v35
	v_div_fmas_f32 v33, v33, v34, v36
	v_div_fixup_f32 v9, v33, v9, v17
	v_div_scale_f32 v17, s[2:3], v8, v8, v30
	v_rcp_f32_e32 v33, v17
	s_nop 0
	v_fma_f32 v34, -v17, v33, 1.0
	v_fmac_f32_e32 v33, v34, v33
	v_div_scale_f32 v34, vcc, v30, v8, v30
	v_mul_f32_e32 v35, v34, v33
	v_fma_f32 v36, -v17, v35, v34
	v_fmac_f32_e32 v35, v36, v33
	v_fma_f32 v17, -v17, v35, v34
	v_div_fmas_f32 v17, v17, v33, v35
	v_div_fixup_f32 v8, v17, v8, v30
	v_mul_f32_e32 v17, 0xbfb8aa3b, v31
	v_exp_f32_e32 v17, v17
	s_nop 0
	v_pk_add_f32 v[16:17], v[16:17], 1.0 op_sel_hi:[1,0]
	s_nop 0
	v_div_scale_f32 v30, s[2:3], v17, v17, v31
	v_rcp_f32_e32 v33, v30
	s_nop 0
	v_fma_f32 v34, -v30, v33, 1.0
	v_fmac_f32_e32 v33, v34, v33
	v_div_scale_f32 v34, vcc, v31, v17, v31
	v_mul_f32_e32 v35, v34, v33
	v_fma_f32 v36, -v30, v35, v34
	v_fmac_f32_e32 v35, v36, v33
	v_fma_f32 v30, -v30, v35, v34
	v_div_fmas_f32 v30, v30, v33, v35
	v_div_fixup_f32 v17, v30, v17, v31
	v_div_scale_f32 v30, s[2:3], v16, v16, v32
	v_rcp_f32_e32 v31, v30
	s_nop 0
	v_fma_f32 v33, -v30, v31, 1.0
	v_fmac_f32_e32 v31, v33, v31
	v_div_scale_f32 v33, vcc, v32, v16, v32
	v_mul_f32_e32 v34, v33, v31
	v_fma_f32 v35, -v30, v34, v33
	v_fmac_f32_e32 v34, v35, v31
	v_fma_f32 v30, -v30, v34, v33
	v_div_fmas_f32 v30, v30, v31, v34
	v_div_fixup_f32 v16, v30, v16, v32
	v_mul_f32_e32 v30, v20, v20
	v_fmac_f32_e32 v30, v18, v18
	v_add_f32_e32 v23, v23, v30
	v_add_f32_e32 v22, v22, v23
	v_add_f32_e32 v13, v13, v22
	v_add_f32_e32 v12, v12, v13
	v_add_f32_e32 v12, v15, v12
	v_add_f32_e32 v12, v14, v12
	ds_bpermute_b32 v13, v114, v12
	s_waitcnt lgkmcnt(0)
	v_add_f32_e32 v12, v12, v13
	ds_bpermute_b32 v13, v115, v12
	s_waitcnt lgkmcnt(0)
	v_add_f32_e32 v12, v12, v13
	ds_bpermute_b32 v13, v116, v12
	s_waitcnt lgkmcnt(0)
	v_add_f32_e32 v12, v12, v13
	ds_bpermute_b32 v13, v117, v12
	s_waitcnt lgkmcnt(0)
	v_add_f32_e32 v12, v12, v13
	v_fmamk_f32 v12, v12, 0x3c000000, v170
	v_cmp_gt_f32_e32 vcc, s94, v12
	v_mul_f32_e32 v13, 0x4b800000, v12
	s_nop 0
	v_cndmask_b32_e32 v12, v12, v13, vcc
	v_rsq_f32_e32 v12, v12
	s_nop 0
	v_mul_f32_e32 v13, 0x45800000, v12
	v_cndmask_b32_e32 v12, v12, v13, vcc
	v_pk_mul_f32 v[18:19], v[18:19], v[12:13] op_sel_hi:[1,0]
	v_pk_mul_f32 v[14:15], v[20:21], v[12:13] op_sel_hi:[1,0]
	v_pk_mul_f32 v[6:7], v[6:7], v[18:19]
	v_mov_b32_e32 v18, v0
	v_pk_mul_f32 v[6:7], v[64:65], v[6:7]
	v_mov_b32_e32 v19, v2
	v_pk_mul_f32 v[4:5], v[4:5], v[6:7]
	v_pk_mul_f32 v[6:7], v[28:29], v[12:13] op_sel_hi:[1,0]
	v_mov_b32_e32 v2, v1
	v_pk_mul_f32 v[6:7], v[18:19], v[6:7]
	v_pk_mul_f32 v[14:15], v[24:25], v[14:15]
	v_pk_mul_f32 v[6:7], v[64:65], v[6:7]
	v_pk_mul_f32 v[14:15], v[64:65], v[14:15]
	v_pk_mul_f32 v[6:7], v[8:9], v[6:7]
	v_pk_mul_f32 v[8:9], v[10:11], v[12:13] op_sel_hi:[1,0]
	v_pk_mul_f32 v[14:15], v[26:27], v[14:15]
	v_pk_mul_f32 v[0:1], v[2:3], v[8:9]
	v_bfe_u32 v8, v5, 16, 1
	v_pk_mul_f32 v[0:1], v[64:65], v[0:1]
	v_bfe_u32 v9, v4, 16, 1
	v_pk_mul_f32 v[0:1], v[16:17], v[0:1]
	v_add3_u32 v4, v4, v9, s15
	v_bfe_u32 v2, v1, 16, 1
	v_bfe_u32 v3, v0, 16, 1
	v_add3_u32 v5, v5, v8, s15
	v_add3_u32 v0, v0, v3, s15
	v_add3_u32 v1, v1, v2, s15
	v_bfe_u32 v2, v14, 16, 1
	v_bfe_u32 v3, v15, 16, 1
	v_bfe_u32 v8, v6, 16, 1
	v_bfe_u32 v9, v7, 16, 1
	v_add3_u32 v7, v7, v9, s15
	v_add3_u32 v6, v6, v8, s15
	v_add3_u32 v3, v15, v3, s15
	v_add3_u32 v2, v14, v2, s15
	v_lshrrev_b32_e32 v8, 16, v2
	v_lshrrev_b32_e32 v9, 16, v3
	v_lshrrev_b32_e32 v2, 16, v6
	v_lshrrev_b32_e32 v3, 16, v7
	v_and_or_b32 v3, v1, s14, v3
	v_and_or_b32 v2, v0, s14, v2
	v_and_or_b32 v1, v5, s14, v9
	v_and_or_b32 v0, v4, s14, v8
	global_store_dwordx4 v[90:91], v[0:3], off offset:-1024
; __device__ __forceinline__ void meta_combine8(const float* __restrict__ ph, int r, int col0, float C, float* out) {
;   float M = -1e30f;
; #pragma unroll
;   for (int sidx = 0; sidx < 8; ++sidx) M = fmaxf(M, ph[(sidx * 16 + r) * 132 + 128]);
;   float l = 0.f, acc[8];
; #pragma unroll
;   for (int i = 0; i < 8; ++i) acc[i] = 0.f;
; #pragma unroll
;   for (int sidx = 0; sidx < 8; ++sidx) { const float* pp = ph + (sidx * 16 + r) * 132; const float w = exp2f((pp[128] - M) * C); l += pp[129] * w;
;     const f32x4 a = *(const f32x4*)(pp + col0), b = *(const f32x4*)(pp + col0 + 4);
;     acc[0] += a.x * w; acc[1] += a.y * w; acc[2] += a.z * w; acc[3] += a.w * w; acc[4] += b.x * w; acc[5] += b.y * w; acc[6] += b.z * w; acc[7] += b.w * w; }
;   const float il = 1.f / l;
; #pragma unroll
;   for (int i = 0; i < 8; ++i) out[i] = acc[i] * il;
; }
; __device__ __forceinline__ void phase_post3(const Params& p, int layer, float lambda_init, const int wave_s) {
;     ...
;       meta_combine8(PART + (size_t)((8 + 2 * h) * 8 * 16) * 132, r, a * 8, 1.f, x1);
.LBB0_829:
	s_andn2_b64 vcc, exec, s[6:7]
	s_cbranch_vccnz .LBB0_826
	s_ashr_i32 s29, s28, 31
	s_lshl_b64 s[38:39], s[28:29], 2
	v_lshl_add_u64 v[0:1], v[68:69], 0, s[38:39]
	v_lshl_add_u64 v[10:11], v[0:1], 0, s[18:19]
	s_mov_b64 s[6:7], 0x4200
	s_mov_b64 s[24:25], 0x6300
	global_load_dwordx2 v[8:9], v[0:1], off offset:512
	global_load_dwordx2 v[12:13], v[10:11], off offset:512
	v_lshl_add_u64 v[16:17], v[0:1], 0, s[6:7]
	v_lshl_add_u64 v[24:25], v[0:1], 0, s[24:25]
	s_mov_b64 s[26:27], 0x8400
	s_mov_b64 s[40:41], 0xa500
	global_load_dwordx2 v[26:27], v[16:17], off offset:512
	global_load_dwordx2 v[28:29], v[24:25], off offset:512
	v_lshl_add_u64 v[32:33], v[0:1], 0, s[26:27]
	v_lshl_add_u64 v[40:41], v[0:1], 0, s[40:41]
	s_mov_b64 s[42:43], 0xc600
	s_mov_b64 s[44:45], 0xe700
	global_load_dwordx2 v[42:43], v[32:33], off offset:512
	global_load_dwordx2 v[44:45], v[40:41], off offset:512
	v_lshl_add_u64 v[48:49], v[0:1], 0, s[42:43]
	v_lshl_add_u64 v[56:57], v[0:1], 0, s[44:45]
	global_load_dwordx2 v[58:59], v[48:49], off offset:512
	global_load_dwordx2 v[60:61], v[56:57], off offset:512
	s_mov_b32 s2, 0xf149f2ca
	v_mov_b32_e32 v89, v169
	v_lshl_add_u64 v[4:5], v[0:1], 0, v[88:89]
	v_lshl_add_u64 v[20:21], v[16:17], 0, v[88:89]
	v_lshl_add_u64 v[36:37], v[32:33], 0, v[88:89]
	v_lshl_add_u64 v[52:53], v[48:49], 0, v[88:89]
	s_waitcnt vmcnt(6)
	v_max3_f32 v2, v8, s2, v12
	s_waitcnt vmcnt(4)
	v_max3_f32 v2, v2, v26, v28
	s_waitcnt vmcnt(2)
	v_max3_f32 v2, v2, v42, v44
	s_waitcnt vmcnt(0)
	v_max3_f32 v62, v2, v58, v60
	v_sub_f32_e32 v2, v8, v62
	v_cmp_gt_f32_e32 vcc, s12, v2
	v_sub_f32_e32 v8, v12, v62
	v_sub_f32_e32 v18, v26, v62
	v_cndmask_b32_e32 v3, 0, v210, vcc
	v_add_f32_e32 v2, v2, v3
	v_cndmask_b32_e32 v3, 0, v211, vcc
	v_cmp_gt_f32_e32 vcc, s12, v8
	v_sub_f32_e32 v26, v28, v62
	v_sub_f32_e32 v34, v42, v62
	v_cndmask_b32_e32 v12, 0, v210, vcc
	v_add_f32_e32 v8, v8, v12
	v_cndmask_b32_e32 v12, 0, v211, vcc
	v_cmp_gt_f32_e32 vcc, s12, v18
	v_sub_f32_e32 v42, v44, v62
	v_exp_f32_e32 v2, v2
	v_cndmask_b32_e32 v19, 0, v210, vcc
	v_add_f32_e32 v18, v18, v19
	v_cndmask_b32_e32 v19, 0, v211, vcc
	v_cmp_gt_f32_e32 vcc, s12, v26
	v_exp_f32_e32 v8, v8
	v_sub_f32_e32 v50, v58, v62
	v_cndmask_b32_e32 v28, 0, v210, vcc
	v_add_f32_e32 v26, v26, v28
	v_cndmask_b32_e32 v28, 0, v211, vcc
	v_cmp_gt_f32_e32 vcc, s12, v34
	v_exp_f32_e32 v18, v18
	v_exp_f32_e32 v26, v26
	v_cndmask_b32_e32 v35, 0, v210, vcc
	v_add_f32_e32 v34, v34, v35
	v_cndmask_b32_e32 v35, 0, v211, vcc
	v_cmp_gt_f32_e32 vcc, s12, v42
	v_sub_f32_e32 v58, v60, v62
	v_ldexp_f32 v94, v2, v3
	v_cndmask_b32_e32 v44, 0, v210, vcc
	v_add_f32_e32 v42, v42, v44
	v_cndmask_b32_e32 v44, 0, v211, vcc
	v_cmp_gt_f32_e32 vcc, s12, v50
	v_ldexp_f32 v95, v8, v12
	v_mov_b32_e32 v12, v9
	v_cndmask_b32_e32 v51, 0, v210, vcc
	v_add_f32_e32 v50, v50, v51
	v_cndmask_b32_e32 v51, 0, v211, vcc
	v_cmp_gt_f32_e32 vcc, s12, v58
	v_exp_f32_e32 v34, v34
	v_exp_f32_e32 v42, v42
	v_cndmask_b32_e32 v60, 0, v210, vcc
	v_pk_mul_f32 v[8:9], v[12:13], v[94:95]
	v_add_f32_e32 v58, v58, v60
	global_load_dwordx4 v[0:3], v[4:5], off offset:16
	s_nop 0
	global_load_dwordx4 v[4:7], v[4:5], off
	v_add_f32_e32 v8, 0, v8
	v_lshl_add_u64 v[12:13], v[10:11], 0, v[88:89]
	v_ldexp_f32 v104, v18, v19
	v_ldexp_f32 v105, v26, v28
	v_mov_b32_e32 v28, v27
	v_exp_f32_e32 v50, v50
	v_exp_f32_e32 v58, v58
	v_add_f32_e32 v30, v8, v9
	global_load_dwordx4 v[8:11], v[12:13], off offset:16
	s_nop 0
	global_load_dwordx4 v[12:15], v[12:13], off
	v_pk_mul_f32 v[26:27], v[104:105], v[28:29]
	global_load_dwordx4 v[16:19], v[20:21], off offset:16
	s_nop 0
	global_load_dwordx4 v[20:23], v[20:21], off
	v_add_f32_e32 v26, v30, v26
	v_lshl_add_u64 v[28:29], v[24:25], 0, v[88:89]
	v_ldexp_f32 v106, v34, v35
	v_ldexp_f32 v107, v42, v44
	v_mov_b32_e32 v44, v43
	v_add_f32_e32 v46, v26, v27
	global_load_dwordx4 v[24:27], v[28:29], off offset:16
	s_nop 0
	global_load_dwordx4 v[28:31], v[28:29], off
	v_pk_mul_f32 v[42:43], v[106:107], v[44:45]
	v_cndmask_b32_e32 v60, 0, v211, vcc
	global_load_dwordx4 v[32:35], v[36:37], off offset:16
	s_nop 0
	global_load_dwordx4 v[36:39], v[36:37], off
	v_add_f32_e32 v42, v46, v42
	v_lshl_add_u64 v[44:45], v[40:41], 0, v[88:89]
	v_ldexp_f32 v108, v50, v51
	v_ldexp_f32 v109, v58, v60
	v_mov_b32_e32 v60, v59
	v_add_f32_e32 v63, v42, v43
	global_load_dwordx4 v[40:43], v[44:45], off offset:16
	s_nop 0
	global_load_dwordx4 v[44:47], v[44:45], off
	v_pk_mul_f32 v[58:59], v[108:109], v[60:61]
	global_load_dwordx4 v[48:51], v[52:53], off offset:16
	s_nop 0
	global_load_dwordx4 v[52:55], v[52:53], off
	v_add_f32_e32 v58, v63, v58
	v_lshl_add_u64 v[60:61], v[56:57], 0, v[88:89]
	v_add_f32_e32 v110, v58, v59
	global_load_dwordx4 v[56:59], v[60:61], off offset:16
	s_nop 0
	global_load_dwordx4 v[60:63], v[60:61], off
	s_waitcnt vmcnt(14)
	v_mov_b32_e32 v100, v4
	v_mov_b32_e32 v101, v6
	v_mov_b32_e32 v6, v5
	v_pk_fma_f32 v[100:101], v[94:95], v[100:101], 0 op_sel_hi:[0,1,0]
	v_mov_b32_e32 v4, v95
	v_pk_fma_f32 v[6:7], v[94:95], v[6:7], 0 op_sel_hi:[0,1,0]
	s_waitcnt vmcnt(12)
	v_mov_b32_e32 v102, v12
	v_mov_b32_e32 v103, v14
	v_mov_b32_e32 v14, v13
	v_pk_fma_f32 v[100:101], v[4:5], v[102:103], v[100:101] op_sel_hi:[0,1,1]
	s_waitcnt vmcnt(10)
	v_mov_b32_e32 v102, v20
	v_mov_b32_e32 v103, v22
	v_pk_fma_f32 v[6:7], v[4:5], v[14:15], v[6:7] op_sel_hi:[0,1,1]
	v_mov_b32_e32 v22, v21
	v_pk_fma_f32 v[100:101], v[104:105], v[102:103], v[100:101] op_sel_hi:[0,1,1]
	v_mov_b32_e32 v12, v105
	s_waitcnt vmcnt(8)
	v_mov_b32_e32 v102, v28
	v_mov_b32_e32 v103, v30
	v_pk_fma_f32 v[6:7], v[104:105], v[22:23], v[6:7] op_sel_hi:[0,1,1]
	v_mov_b32_e32 v30, v29
	v_pk_fma_f32 v[100:101], v[12:13], v[102:103], v[100:101] op_sel_hi:[0,1,1]
	s_waitcnt vmcnt(6)
; __device__ __forceinline__ void meta_combine8(const float* __restrict__ ph, int r, int col0, float C, float* out) {
;   float M = -1e30f;
; #pragma unroll
;   for (int sidx = 0; sidx < 8; ++sidx) M = fmaxf(M, ph[(sidx * 16 + r) * 132 + 128]);
;   float l = 0.f, acc[8];
; #pragma unroll
;   for (int i = 0; i < 8; ++i) acc[i] = 0.f;
; #pragma unroll
;   for (int sidx = 0; sidx < 8; ++sidx) { const float* pp = ph + (sidx * 16 + r) * 132; const float w = exp2f((pp[128] - M) * C); l += pp[129] * w;
;     const f32x4 a = *(const f32x4*)(pp + col0), b = *(const f32x4*)(pp + col0 + 4);
;     acc[0] += a.x * w; acc[1] += a.y * w; acc[2] += a.z * w; acc[3] += a.w * w; acc[4] += b.x * w; acc[5] += b.y * w; acc[6] += b.z * w; acc[7] += b.w * w; }
;   const float il = 1.f / l;
; #pragma unroll
;   for (int i = 0; i < 8; ++i) out[i] = acc[i] * il;
; }
; __device__ __forceinline__ void phase_post3(const Params& p, int layer, float lambda_init, const int wave_s) {
;     ...
;       meta_combine8(PART + (size_t)((8 + 2 * h) * 8 * 16) * 132, r, a * 8, 1.f, x1);
;       meta_combine8(PART + (size_t)((8 + 2 * h + 1) * 8 * 16) * 132, r, a * 8, 1.f, x2);
	v_mov_b32_e32 v102, v36
	v_mov_b32_e32 v103, v38
	v_pk_fma_f32 v[6:7], v[12:13], v[30:31], v[6:7] op_sel_hi:[0,1,1]
	v_mov_b32_e32 v38, v37
	v_pk_fma_f32 v[100:101], v[106:107], v[102:103], v[100:101] op_sel_hi:[0,1,1]
	v_mov_b32_e32 v20, v107
	s_waitcnt vmcnt(4)
	v_mov_b32_e32 v102, v44
	v_mov_b32_e32 v103, v46
	v_pk_fma_f32 v[6:7], v[106:107], v[38:39], v[6:7] op_sel_hi:[0,1,1]
	v_mov_b32_e32 v46, v45
	v_pk_fma_f32 v[100:101], v[20:21], v[102:103], v[100:101] op_sel_hi:[0,1,1]
	s_waitcnt vmcnt(2)
	v_mov_b32_e32 v102, v52
	v_mov_b32_e32 v103, v54
	v_pk_fma_f32 v[6:7], v[20:21], v[46:47], v[6:7] op_sel_hi:[0,1,1]
	v_mov_b32_e32 v54, v53
	v_pk_fma_f32 v[100:101], v[108:109], v[102:103], v[100:101] op_sel_hi:[0,1,1]
	v_mov_b32_e32 v28, v109
	s_waitcnt vmcnt(0)
	v_mov_b32_e32 v102, v60
	v_mov_b32_e32 v103, v62
	v_pk_fma_f32 v[6:7], v[108:109], v[54:55], v[6:7] op_sel_hi:[0,1,1]
	v_mov_b32_e32 v62, v61
	v_pk_fma_f32 v[100:101], v[28:29], v[102:103], v[100:101] op_sel_hi:[0,1,1]
	v_pk_fma_f32 v[102:103], v[28:29], v[62:63], v[6:7] op_sel_hi:[0,1,1]
	v_mov_b32_e32 v6, v0
	v_mov_b32_e32 v7, v2
	v_mov_b32_e32 v2, v1
	v_pk_fma_f32 v[6:7], v[94:95], v[6:7], 0 op_sel_hi:[0,1,0]
	v_mov_b32_e32 v14, v8
	v_mov_b32_e32 v15, v10
	v_pk_fma_f32 v[0:1], v[94:95], v[2:3], 0 op_sel_hi:[0,1,0]
	v_mov_b32_e32 v10, v9
	v_pk_fma_f32 v[6:7], v[4:5], v[14:15], v[6:7] op_sel_hi:[0,1,1]
	v_mov_b32_e32 v14, v16
	v_mov_b32_e32 v15, v18
	v_pk_fma_f32 v[0:1], v[4:5], v[10:11], v[0:1] op_sel_hi:[0,1,1]
	v_mov_b32_e32 v18, v17
	v_pk_fma_f32 v[6:7], v[104:105], v[14:15], v[6:7] op_sel_hi:[0,1,1]
	v_mov_b32_e32 v14, v24
	v_mov_b32_e32 v15, v26
	v_pk_fma_f32 v[0:1], v[104:105], v[18:19], v[0:1] op_sel_hi:[0,1,1]
	v_mov_b32_e32 v26, v25
	v_pk_fma_f32 v[6:7], v[12:13], v[14:15], v[6:7] op_sel_hi:[0,1,1]
	v_mov_b32_e32 v14, v32
	v_mov_b32_e32 v15, v34
	v_pk_fma_f32 v[0:1], v[12:13], v[26:27], v[0:1] op_sel_hi:[0,1,1]
	v_mov_b32_e32 v34, v33
	v_pk_fma_f32 v[6:7], v[106:107], v[14:15], v[6:7] op_sel_hi:[0,1,1]
	v_mov_b32_e32 v14, v40
	v_mov_b32_e32 v15, v42
	v_pk_fma_f32 v[0:1], v[106:107], v[34:35], v[0:1] op_sel_hi:[0,1,1]
	v_mov_b32_e32 v42, v41
	v_pk_fma_f32 v[6:7], v[20:21], v[14:15], v[6:7] op_sel_hi:[0,1,1]
	v_mov_b32_e32 v14, v48
	v_mov_b32_e32 v15, v50
	v_pk_fma_f32 v[0:1], v[20:21], v[42:43], v[0:1] op_sel_hi:[0,1,1]
	v_mov_b32_e32 v50, v49
	v_pk_fma_f32 v[6:7], v[108:109], v[14:15], v[6:7] op_sel_hi:[0,1,1]
	v_mov_b32_e32 v15, v58
	v_pk_fma_f32 v[0:1], v[108:109], v[50:51], v[0:1] op_sel_hi:[0,1,1]
	v_mov_b32_e32 v58, v57
	v_pk_fma_f32 v[62:63], v[28:29], v[58:59], v[0:1] op_sel_hi:[0,1,1]
	v_div_scale_f32 v0, s[0:1], v110, v110, 1.0
	v_rcp_f32_e32 v1, v0
	v_mov_b32_e32 v14, v56
	v_pk_fma_f32 v[60:61], v[28:29], v[14:15], v[6:7] op_sel_hi:[0,1,1]
	v_fma_f32 v2, -v0, v1, 1.0
	v_fmac_f32_e32 v1, v2, v1
	v_div_scale_f32 v2, vcc, 1.0, v110, 1.0
	v_mul_f32_e32 v3, v2, v1
	v_fma_f32 v4, -v0, v3, v2
	v_fmac_f32_e32 v3, v4, v1
	v_fma_f32 v0, -v0, v3, v2
	v_div_fmas_f32 v0, v0, v1, v3
	v_div_fixup_f32 v94, v0, v110, 1.0
	v_lshl_add_u64 v[0:1], v[70:71], 0, s[38:39]
	v_lshl_add_u64 v[4:5], v[0:1], 0, s[18:19]
	global_load_dwordx2 v[6:7], v[0:1], off offset:512
	global_load_dwordx2 v[14:15], v[4:5], off offset:512
	v_lshl_add_u64 v[12:13], v[0:1], 0, s[6:7]
	v_lshl_add_u64 v[24:25], v[0:1], 0, s[24:25]
	global_load_dwordx2 v[26:27], v[12:13], off offset:512
	global_load_dwordx2 v[30:31], v[24:25], off offset:512
	v_lshl_add_u64 v[28:29], v[0:1], 0, s[26:27]
	v_lshl_add_u64 v[40:41], v[0:1], 0, s[40:41]
	global_load_dwordx2 v[42:43], v[28:29], off offset:512
	global_load_dwordx2 v[46:47], v[40:41], off offset:512
	v_lshl_add_u64 v[44:45], v[0:1], 0, s[42:43]
	v_lshl_add_u64 v[56:57], v[0:1], 0, s[44:45]
	global_load_dwordx2 v[58:59], v[44:45], off offset:512
	global_load_dwordx2 v[104:105], v[56:57], off offset:512
	v_lshl_add_u64 v[8:9], v[0:1], 0, v[88:89]
	v_lshl_add_u64 v[20:21], v[12:13], 0, v[88:89]
	v_lshl_add_u64 v[36:37], v[28:29], 0, v[88:89]
	v_lshl_add_u64 v[52:53], v[44:45], 0, v[88:89]
	s_waitcnt vmcnt(6)
	v_max3_f32 v2, v6, s2, v14
	s_waitcnt vmcnt(4)
	v_max3_f32 v2, v2, v26, v30
	s_waitcnt vmcnt(2)
	v_max3_f32 v2, v2, v42, v46
	s_waitcnt vmcnt(0)
	v_max3_f32 v95, v2, v58, v104
	v_sub_f32_e32 v2, v6, v95
	v_cmp_gt_f32_e32 vcc, s12, v2
	v_sub_f32_e32 v6, v14, v95
	s_nop 0
	v_cndmask_b32_e32 v3, 0, v210, vcc
	v_add_f32_e32 v2, v2, v3
	v_cndmask_b32_e32 v3, 0, v211, vcc
	v_cmp_gt_f32_e32 vcc, s12, v6
	v_exp_f32_e32 v2, v2
	s_nop 0
	v_cndmask_b32_e32 v14, 0, v210, vcc
	v_add_f32_e32 v6, v6, v14
	v_exp_f32_e32 v6, v6
	v_cndmask_b32_e32 v14, 0, v211, vcc
	v_ldexp_f32 v106, v2, v3
	global_load_dwordx4 v[0:3], v[8:9], off offset:16
	s_nop 0
	global_load_dwordx4 v[8:11], v[8:9], off
	v_ldexp_f32 v107, v6, v14
	v_mov_b32_e32 v14, v7
	v_pk_mul_f32 v[6:7], v[14:15], v[106:107]
	v_lshl_add_u64 v[14:15], v[4:5], 0, v[88:89]
	v_add_f32_e32 v6, 0, v6
	v_add_f32_e32 v32, v6, v7
	global_load_dwordx4 v[4:7], v[14:15], off offset:16
	global_load_dwordx4 v[16:19], v[14:15], off
	v_sub_f32_e32 v14, v26, v95
	v_cmp_gt_f32_e32 vcc, s12, v14
	v_sub_f32_e32 v26, v30, v95
	s_waitcnt vmcnt(0)
; __device__ __forceinline__ void meta_combine8(const float* __restrict__ ph, int r, int col0, float C, float* out) {
;   float M = -1e30f;
; #pragma unroll
;   for (int sidx = 0; sidx < 8; ++sidx) M = fmaxf(M, ph[(sidx * 16 + r) * 132 + 128]);
;   float l = 0.f, acc[8];
; #pragma unroll
;   for (int i = 0; i < 8; ++i) acc[i] = 0.f;
; #pragma unroll
;   for (int sidx = 0; sidx < 8; ++sidx) { const float* pp = ph + (sidx * 16 + r) * 132; const float w = exp2f((pp[128] - M) * C); l += pp[129] * w;
;     const f32x4 a = *(const f32x4*)(pp + col0), b = *(const f32x4*)(pp + col0 + 4);
;     acc[0] += a.x * w; acc[1] += a.y * w; acc[2] += a.z * w; acc[3] += a.w * w; acc[4] += b.x * w; acc[5] += b.y * w; acc[6] += b.z * w; acc[7] += b.w * w; }
;   const float il = 1.f / l;
; #pragma unroll
;   for (int i = 0; i < 8; ++i) out[i] = acc[i] * il;
; }
	v_mov_b32_e32 v125, v18
	v_cndmask_b32_e32 v15, 0, v210, vcc
	v_add_f32_e32 v14, v14, v15
	v_cndmask_b32_e32 v15, 0, v211, vcc
	v_cmp_gt_f32_e32 vcc, s12, v26
	v_exp_f32_e32 v14, v14
	v_mov_b32_e32 v18, v17
	v_cndmask_b32_e32 v30, 0, v210, vcc
	v_add_f32_e32 v26, v26, v30
	v_exp_f32_e32 v26, v26
	v_cndmask_b32_e32 v30, 0, v211, vcc
	v_ldexp_f32 v108, v14, v15
	global_load_dwordx4 v[12:15], v[20:21], off offset:16
	s_nop 0
	global_load_dwordx4 v[20:23], v[20:21], off
	v_ldexp_f32 v109, v26, v30
	v_mov_b32_e32 v30, v27
	v_pk_mul_f32 v[26:27], v[108:109], v[30:31]
	v_lshl_add_u64 v[30:31], v[24:25], 0, v[88:89]
	v_add_f32_e32 v26, v32, v26
	v_add_f32_e32 v48, v26, v27
	global_load_dwordx4 v[24:27], v[30:31], off offset:16
	global_load_dwordx4 v[32:35], v[30:31], off
	v_sub_f32_e32 v30, v42, v95
	v_cmp_gt_f32_e32 vcc, s12, v30
	v_sub_f32_e32 v42, v46, v95
	v_mov_b32_e32 v17, v2
	v_cndmask_b32_e32 v31, 0, v210, vcc
	v_add_f32_e32 v30, v30, v31
	v_cndmask_b32_e32 v31, 0, v211, vcc
	v_cmp_gt_f32_e32 vcc, s12, v42
	v_exp_f32_e32 v30, v30
	v_mov_b32_e32 v2, v1
	v_cndmask_b32_e32 v46, 0, v210, vcc
	v_add_f32_e32 v42, v42, v46
	v_exp_f32_e32 v42, v42
	v_cndmask_b32_e32 v46, 0, v211, vcc
	v_ldexp_f32 v110, v30, v31
	global_load_dwordx4 v[28:31], v[36:37], off offset:16
	s_nop 0
	global_load_dwordx4 v[36:39], v[36:37], off
	v_ldexp_f32 v111, v42, v46
	v_mov_b32_e32 v46, v43
	v_pk_mul_f32 v[42:43], v[110:111], v[46:47]
	v_lshl_add_u64 v[46:47], v[40:41], 0, v[88:89]
	v_add_f32_e32 v42, v48, v42
	v_add_f32_e32 v118, v42, v43
	global_load_dwordx4 v[40:43], v[46:47], off offset:16
	global_load_dwordx4 v[48:51], v[46:47], off
	v_sub_f32_e32 v46, v58, v95
	v_cmp_gt_f32_e32 vcc, s12, v46
	v_sub_f32_e32 v58, v104, v95
	v_mov_b32_e32 v104, v59
	v_cndmask_b32_e32 v47, 0, v210, vcc
	v_add_f32_e32 v46, v46, v47
	v_cndmask_b32_e32 v47, 0, v211, vcc
	v_cmp_gt_f32_e32 vcc, s12, v58
	v_exp_f32_e32 v46, v46
	s_nop 0
	v_cndmask_b32_e32 v95, 0, v210, vcc
	v_add_f32_e32 v58, v58, v95
	v_exp_f32_e32 v58, v58
	v_cndmask_b32_e32 v95, 0, v211, vcc
	v_ldexp_f32 v112, v46, v47
	global_load_dwordx4 v[44:47], v[52:53], off offset:16
	s_nop 0
	global_load_dwordx4 v[52:55], v[52:53], off
	v_ldexp_f32 v113, v58, v95
	v_pk_mul_f32 v[58:59], v[112:113], v[104:105]
	v_lshl_add_u64 v[104:105], v[56:57], 0, v[88:89]
	v_add_f32_e32 v58, v118, v58
	v_add_f32_e32 v95, v58, v59
	global_load_dwordx4 v[56:59], v[104:105], off offset:16
	global_load_dwordx4 v[118:121], v[104:105], off
	v_div_scale_f32 v104, s[0:1], v95, v95, 1.0
	v_rcp_f32_e32 v105, v104
	s_nop 0
	v_fma_f32 v122, -v104, v105, 1.0
	v_fmac_f32_e32 v105, v122, v105
	v_div_scale_f32 v122, vcc, 1.0, v95, 1.0
	v_mul_f32_e32 v123, v122, v105
	v_fma_f32 v124, -v104, v123, v122
	v_fmac_f32_e32 v123, v124, v105
	v_fma_f32 v104, -v104, v123, v122
	v_div_fmas_f32 v104, v104, v105, v123
	v_mov_b32_e32 v105, v10
	v_mov_b32_e32 v10, v9
	v_div_fixup_f32 v122, v104, v95, 1.0
	v_mov_b32_e32 v104, v8
	v_mov_b32_e32 v8, v107
	v_mov_b32_e32 v124, v16
	v_pk_fma_f32 v[10:11], v[106:107], v[10:11], 0 op_sel_hi:[0,1,0]
	v_mov_b32_e32 v16, v0
	v_pk_fma_f32 v[10:11], v[8:9], v[18:19], v[10:11] op_sel_hi:[0,1,1]
	v_pk_fma_f32 v[16:17], v[106:107], v[16:17], 0 op_sel_hi:[0,1,0]
	v_mov_b32_e32 v18, v4
	v_mov_b32_e32 v19, v6
	v_pk_fma_f32 v[0:1], v[106:107], v[2:3], 0 op_sel_hi:[0,1,0]
	v_mov_b32_e32 v6, v5
	v_pk_fma_f32 v[104:105], v[106:107], v[104:105], 0 op_sel_hi:[0,1,0]
	v_pk_fma_f32 v[16:17], v[8:9], v[18:19], v[16:17] op_sel_hi:[0,1,1]
	s_waitcnt vmcnt(11)
	v_mov_b32_e32 v18, v12
	v_mov_b32_e32 v19, v14
	v_pk_fma_f32 v[0:1], v[8:9], v[6:7], v[0:1] op_sel_hi:[0,1,1]
	v_mov_b32_e32 v14, v13
	v_pk_fma_f32 v[104:105], v[8:9], v[124:125], v[104:105] op_sel_hi:[0,1,1]
	s_waitcnt vmcnt(10)
	v_mov_b32_e32 v124, v20
	v_mov_b32_e32 v20, v109
	v_pk_fma_f32 v[16:17], v[108:109], v[18:19], v[16:17] op_sel_hi:[0,1,1]
	s_waitcnt vmcnt(9)
; __device__ __forceinline__ float silu(float g) { return g / (1.f + __expf(-g)); }
; __device__ __forceinline__ float sum16(float v) { v += __shfl_xor(v, 1); v += __shfl_xor(v, 2); v += __shfl_xor(v, 4); v += __shfl_xor(v, 8); return v; }
; __device__ __forceinline__ void unpack8(const u32x4 w, float* x) { x[0] = bflo(w.x); x[1] = bfhi(w.x); x[2] = bflo(w.y); x[3] = bfhi(w.y); x[4] = bflo(w.z); x[5] = bfhi(w.z); x[6] = bflo(w.w); x[7] = bfhi(w.w); }
; __device__ __forceinline__ void phase_post3(const Params& p, int layer, float lambda_init, const int wave_s) {
;     ...
;       float x[8], ss = 0.f;
; #pragma unroll
;       for (int i = 0; i < 8; ++i) { x[i] = x1[i] - lam * x2[i]; ss += x[i] * x[i]; }
;       const float rs = rsqrtf(sum16(ss) * (1.f / 128.f) + EPS);
;       float g[8]; unpack8(*(const u32x4*)(P + (size_t)r * INP + C_AG + h * 128 + a * 8), g);
; #pragma unroll
;       for (int i = 0; i < 8; ++i) x[i] = x[i] * rs * sub[a * 8 + i] * post * silu(g[i]);
	v_mov_b32_e32 v18, v24
	v_mov_b32_e32 v19, v26
	v_pk_fma_f32 v[0:1], v[108:109], v[14:15], v[0:1] op_sel_hi:[0,1,1]
	v_mov_b32_e32 v26, v25
	v_mov_b32_e32 v125, v22
	v_pk_fma_f32 v[16:17], v[20:21], v[18:19], v[16:17] op_sel_hi:[0,1,1]
	v_pk_fma_f32 v[0:1], v[20:21], v[26:27], v[0:1] op_sel_hi:[0,1,1]
	v_pk_fma_f32 v[104:105], v[108:109], v[124:125], v[104:105] op_sel_hi:[0,1,1]
	s_waitcnt vmcnt(8)
	v_mov_b32_e32 v124, v32
	v_mov_b32_e32 v32, v111
	s_waitcnt vmcnt(7)
	v_mov_b32_e32 v18, v28
	v_mov_b32_e32 v19, v30
	v_mov_b32_e32 v30, v29
	v_pk_fma_f32 v[16:17], v[110:111], v[18:19], v[16:17] op_sel_hi:[0,1,1]
	v_pk_fma_f32 v[0:1], v[110:111], v[30:31], v[0:1] op_sel_hi:[0,1,1]
	v_mov_b32_e32 v125, v34
	v_pk_fma_f32 v[104:105], v[20:21], v[124:125], v[104:105] op_sel_hi:[0,1,1]
	s_waitcnt vmcnt(5)
	v_mov_b32_e32 v18, v40
	v_mov_b32_e32 v19, v42
	v_mov_b32_e32 v42, v41
	v_pk_fma_f32 v[16:17], v[32:33], v[18:19], v[16:17] op_sel_hi:[0,1,1]
	v_pk_fma_f32 v[0:1], v[32:33], v[42:43], v[0:1] op_sel_hi:[0,1,1]
	v_mov_b32_e32 v124, v36
	v_mov_b32_e32 v36, v113
	v_mov_b32_e32 v22, v21
	v_mov_b32_e32 v125, v38
	v_pk_fma_f32 v[10:11], v[108:109], v[22:23], v[10:11] op_sel_hi:[0,1,1]
	v_mov_b32_e32 v34, v33
	v_pk_fma_f32 v[104:105], v[110:111], v[124:125], v[104:105] op_sel_hi:[0,1,1]
	s_waitcnt vmcnt(4)
	v_mov_b32_e32 v124, v48
	v_mov_b32_e32 v125, v50
	v_pk_fma_f32 v[10:11], v[20:21], v[34:35], v[10:11] op_sel_hi:[0,1,1]
	v_mov_b32_e32 v38, v37
	s_waitcnt vmcnt(3)
	v_mov_b32_e32 v18, v44
	v_mov_b32_e32 v19, v46
	v_mov_b32_e32 v46, v45
	v_pk_fma_f32 v[16:17], v[112:113], v[18:19], v[16:17] op_sel_hi:[0,1,1]
	v_pk_fma_f32 v[0:1], v[112:113], v[46:47], v[0:1] op_sel_hi:[0,1,1]
	v_pk_fma_f32 v[104:105], v[32:33], v[124:125], v[104:105] op_sel_hi:[0,1,1]
	s_waitcnt vmcnt(1)
	v_mov_b32_e32 v19, v58
	v_mov_b32_e32 v58, v57
	v_pk_fma_f32 v[0:1], v[36:37], v[58:59], v[0:1] op_sel_hi:[0,1,1]
	v_pk_mul_f32 v[14:15], v[122:123], v[0:1] op_sel_hi:[0,1]
	v_add_co_u32_e32 v0, vcc, s4, v92
	v_mov_b32_e32 v124, v52
	s_nop 0
	v_addc_co_u32_e32 v1, vcc, 0, v93, vcc
	global_load_dwordx4 v[6:9], v[0:1], off offset:3072
	v_mov_b32_e32 v125, v54
	v_pk_fma_f32 v[10:11], v[110:111], v[38:39], v[10:11] op_sel_hi:[0,1,1]
	v_mov_b32_e32 v50, v49
	v_pk_fma_f32 v[104:105], v[112:113], v[124:125], v[104:105] op_sel_hi:[0,1,1]
	s_waitcnt vmcnt(1)
	v_mov_b32_e32 v124, v118
	v_mov_b32_e32 v125, v120
	v_pk_fma_f32 v[10:11], v[32:33], v[50:51], v[10:11] op_sel_hi:[0,1,1]
	v_mov_b32_e32 v54, v53
	v_pk_fma_f32 v[104:105], v[36:37], v[124:125], v[104:105] op_sel_hi:[0,1,1]
	v_pk_fma_f32 v[10:11], v[112:113], v[54:55], v[10:11] op_sel_hi:[0,1,1]
	v_mov_b32_e32 v120, v119
	v_pk_mul_f32 v[104:105], v[122:123], v[104:105] op_sel_hi:[0,1]
	v_pk_fma_f32 v[10:11], v[36:37], v[120:121], v[10:11] op_sel_hi:[0,1,1]
	v_pk_mul_f32 v[10:11], v[122:123], v[10:11] op_sel_hi:[0,1]
	v_pk_mul_f32 v[0:1], v[66:67], v[104:105]
	v_mov_b32_e32 v18, v56
	v_pk_fma_f32 v[12:13], v[94:95], v[100:101], v[0:1] op_sel_hi:[0,1,1] neg_lo:[0,0,1] neg_hi:[0,0,1]
	v_pk_mul_f32 v[0:1], v[66:67], v[10:11]
	v_pk_fma_f32 v[16:17], v[36:37], v[18:19], v[16:17] op_sel_hi:[0,1,1]
	v_pk_fma_f32 v[10:11], v[94:95], v[102:103], v[0:1] op_sel_hi:[0,1,1] neg_lo:[0,0,1] neg_hi:[0,0,1]
	v_mov_b32_e32 v0, v11
	v_mov_b32_e32 v1, v13
	v_pk_mul_f32 v[18:19], v[0:1], v[0:1]
	v_pk_mul_f32 v[16:17], v[122:123], v[16:17] op_sel_hi:[0,1]
	v_pk_mul_f32 v[16:17], v[66:67], v[16:17]
	v_pk_mul_f32 v[14:15], v[66:67], v[14:15]
	v_pk_fma_f32 v[16:17], v[94:95], v[60:61], v[16:17] op_sel_hi:[0,1,1] neg_lo:[0,0,1] neg_hi:[0,0,1]
	v_pk_fma_f32 v[14:15], v[94:95], v[62:63], v[14:15] op_sel_hi:[0,1,1] neg_lo:[0,0,1] neg_hi:[0,0,1]
	s_waitcnt vmcnt(0)
	v_lshlrev_b32_e32 v28, 16, v6
	v_and_b32_e32 v26, 0xffff0000, v6
	v_mul_f32_e32 v0, 0xbfb8aa3b, v28
	v_exp_f32_e32 v22, v0
	v_mul_f32_e32 v0, 0xbfb8aa3b, v26
	v_lshlrev_b32_e32 v25, 16, v7
	v_and_b32_e32 v27, 0xffff0000, v7
	v_exp_f32_e32 v24, v0
	v_mov_b32_e32 v0, v134
	v_mov_b32_e32 v1, v135
	v_mov_b32_e32 v2, v136
	v_mov_b32_e32 v3, v137
	v_mov_b32_e32 v4, v138
	v_mov_b32_e32 v5, v139
	v_mov_b32_e32 v6, v140
	v_mov_b32_e32 v7, v141
	v_and_b32_e32 v32, 0xffff0000, v8

; __device__ __forceinline__ float silu(float g) { return g / (1.f + __expf(-g)); }
; __device__ __forceinline__ float sum16(float v) { v += __shfl_xor(v, 1); v += __shfl_xor(v, 2); v += __shfl_xor(v, 4); v += __shfl_xor(v, 8); return v; }
; __device__ __forceinline__ void unpack8(const u32x4 w, float* x) { x[0] = bflo(w.x); x[1] = bfhi(w.x); x[2] = bflo(w.y); x[3] = bfhi(w.y); x[4] = bflo(w.z); x[5] = bfhi(w.z); x[6] = bflo(w.w); x[7] = bfhi(w.w); }
; __device__ __forceinline__ void phase_post3(const Params& p, int layer, float lambda_init, const int wave_s) {
;     ...
;       const float rs = rsqrtf(sum16(ss) * (1.f / 128.f) + EPS);
;       float g[8]; unpack8(*(const u32x4*)(P + (size_t)r * INP + C_AG + h * 128 + a * 8), g);
; #pragma unroll
;       for (int i = 0; i < 8; ++i) x[i] = x[i] * rs * sub[a * 8 + i] * post * silu(g[i]);
	v_mov_b32_e32 v20, v4
	v_mul_f32_e32 v4, 0xbfb8aa3b, v25
	v_exp_f32_e32 v23, v4
	v_mov_b32_e32 v21, v6
	v_pk_add_f32 v[22:23], v[22:23], 1.0 op_sel_hi:[1,0]
	s_nop 0
	v_div_scale_f32 v4, s[0:1], v23, v23, v25
	v_rcp_f32_e32 v6, v4
	s_nop 0
	v_fma_f32 v29, -v4, v6, 1.0
	v_fmac_f32_e32 v6, v29, v6
	v_div_scale_f32 v29, vcc, v25, v23, v25
	v_mul_f32_e32 v30, v29, v6
	v_fma_f32 v31, -v4, v30, v29
	v_fmac_f32_e32 v30, v31, v6
	v_fma_f32 v4, -v4, v30, v29
	v_div_fmas_f32 v4, v4, v6, v30
	v_div_fixup_f32 v23, v4, v23, v25
	v_div_scale_f32 v4, s[0:1], v22, v22, v28
	v_rcp_f32_e32 v6, v4
	v_and_b32_e32 v31, 0xffff0000, v9
	v_fma_f32 v25, -v4, v6, 1.0
	v_fmac_f32_e32 v6, v25, v6
	v_div_scale_f32 v25, vcc, v28, v22, v28
	v_mul_f32_e32 v29, v25, v6
	v_fma_f32 v30, -v4, v29, v25
	v_fmac_f32_e32 v29, v30, v6
	v_fma_f32 v4, -v4, v29, v25
	v_div_fmas_f32 v4, v4, v6, v29
	v_div_fixup_f32 v22, v4, v22, v28
	v_mul_f32_e32 v4, 0xbfb8aa3b, v27
	v_exp_f32_e32 v25, v4
	v_mov_b32_e32 v6, v5
	v_pk_add_f32 v[4:5], v[24:25], 1.0 op_sel_hi:[1,0]
	s_nop 0
	v_div_scale_f32 v24, s[0:1], v5, v5, v27
	v_rcp_f32_e32 v25, v24
	s_nop 0
	v_fma_f32 v28, -v24, v25, 1.0
	v_fmac_f32_e32 v25, v28, v25
	v_div_scale_f32 v28, vcc, v27, v5, v27
	v_mul_f32_e32 v29, v28, v25
	v_fma_f32 v30, -v24, v29, v28
	v_fmac_f32_e32 v29, v30, v25
	v_fma_f32 v24, -v24, v29, v28
	v_div_fmas_f32 v24, v24, v25, v29
	v_div_fixup_f32 v5, v24, v5, v27
	v_div_scale_f32 v24, s[0:1], v4, v4, v26
	v_rcp_f32_e32 v25, v24
	v_lshlrev_b32_e32 v30, 16, v8
	v_mul_f32_e32 v8, 0xbfb8aa3b, v30
	v_exp_f32_e32 v8, v8
	v_fma_f32 v27, -v24, v25, 1.0
	v_fmac_f32_e32 v25, v27, v25
	v_div_scale_f32 v27, vcc, v26, v4, v26
	v_mul_f32_e32 v28, v27, v25
	v_fma_f32 v29, -v24, v28, v27
	v_fmac_f32_e32 v28, v29, v25
	v_fma_f32 v24, -v24, v28, v27
	v_lshlrev_b32_e32 v29, 16, v9
	v_mul_f32_e32 v9, 0xbfb8aa3b, v32
	v_div_fmas_f32 v24, v24, v25, v28
	v_exp_f32_e32 v28, v9
	v_mul_f32_e32 v9, 0xbfb8aa3b, v29
	v_exp_f32_e32 v9, v9
	v_div_fixup_f32 v4, v24, v4, v26
	v_mov_b32_e32 v24, v14
	v_mov_b32_e32 v25, v16
	v_pk_add_f32 v[8:9], v[8:9], 1.0 op_sel_hi:[1,0]
	v_pk_mul_f32 v[24:25], v[24:25], v[24:25]
	v_div_scale_f32 v33, s[0:1], v9, v9, v29
	v_rcp_f32_e32 v34, v33
	v_mov_b32_e32 v26, v15
	v_mov_b32_e32 v27, v17
	v_pk_mul_f32 v[26:27], v[26:27], v[26:27]
	v_fma_f32 v35, -v33, v34, 1.0
	v_fmac_f32_e32 v34, v35, v34
	v_div_scale_f32 v35, vcc, v29, v9, v29
	v_mul_f32_e32 v36, v35, v34
	v_fma_f32 v37, -v33, v36, v35
	v_fmac_f32_e32 v36, v37, v34
	v_fma_f32 v33, -v33, v36, v35
	v_div_fmas_f32 v33, v33, v34, v36
	v_div_fixup_f32 v9, v33, v9, v29
	v_div_scale_f32 v29, s[0:1], v8, v8, v30
	v_rcp_f32_e32 v33, v29
	s_nop 0
	v_fma_f32 v34, -v29, v33, 1.0
	v_fmac_f32_e32 v33, v34, v33
	v_div_scale_f32 v34, vcc, v30, v8, v30
	v_mul_f32_e32 v35, v34, v33
	v_fma_f32 v36, -v29, v35, v34
	v_fmac_f32_e32 v35, v36, v33
	v_fma_f32 v29, -v29, v35, v34
	v_div_fmas_f32 v29, v29, v33, v35
	v_div_fixup_f32 v8, v29, v8, v30
	v_mul_f32_e32 v29, 0xbfb8aa3b, v31
	v_exp_f32_e32 v29, v29
	s_nop 0
	v_pk_add_f32 v[28:29], v[28:29], 1.0 op_sel_hi:[1,0]
	s_nop 0
	v_div_scale_f32 v30, s[0:1], v29, v29, v31
	v_rcp_f32_e32 v33, v30
	s_nop 0
	v_fma_f32 v34, -v30, v33, 1.0
	v_fmac_f32_e32 v33, v34, v33
	v_div_scale_f32 v34, vcc, v31, v29, v31
	v_mul_f32_e32 v35, v34, v33
	v_fma_f32 v36, -v30, v35, v34
	v_fmac_f32_e32 v35, v36, v33
	v_fma_f32 v30, -v30, v35, v34
	v_div_fmas_f32 v30, v30, v33, v35
	v_div_fixup_f32 v29, v30, v29, v31
	v_div_scale_f32 v30, s[0:1], v28, v28, v32
	v_rcp_f32_e32 v31, v30
	s_nop 0
	v_fma_f32 v33, -v30, v31, 1.0
	v_fmac_f32_e32 v31, v33, v31
	v_div_scale_f32 v33, vcc, v32, v28, v32
	v_mul_f32_e32 v34, v33, v31
	v_fma_f32 v35, -v30, v34, v33
	v_fmac_f32_e32 v34, v35, v31
	v_fma_f32 v30, -v30, v34, v33
	v_div_fmas_f32 v30, v30, v31, v34
	v_div_fixup_f32 v28, v30, v28, v32
	v_mul_f32_e32 v30, v12, v12
	v_fmac_f32_e32 v30, v10, v10
	v_add_f32_e32 v19, v19, v30
	v_add_f32_e32 v18, v18, v19
	v_add_f32_e32 v18, v25, v18
	v_add_f32_e32 v18, v24, v18
	v_add_f32_e32 v18, v27, v18
	v_add_f32_e32 v18, v26, v18
	ds_bpermute_b32 v19, v114, v18
	s_waitcnt lgkmcnt(0)
	v_add_f32_e32 v18, v18, v19
	ds_bpermute_b32 v19, v115, v18
	s_waitcnt lgkmcnt(0)
	v_add_f32_e32 v18, v18, v19
	ds_bpermute_b32 v19, v116, v18
	s_waitcnt lgkmcnt(0)
	v_add_f32_e32 v18, v18, v19
	ds_bpermute_b32 v19, v117, v18
	s_waitcnt lgkmcnt(0)
; __device__ __forceinline__ float silu(float g) { return g / (1.f + __expf(-g)); }
; __device__ __forceinline__ u32x4 pack8(const float* x) { u32x4 w; w.x = pk2(x[0], x[1]); w.y = pk2(x[2], x[3]); w.z = pk2(x[4], x[5]); w.w = pk2(x[6], x[7]); return w; }
; __device__ __forceinline__ void meta_combine8(const float* __restrict__ ph, int r, int col0, float C, float* out) {
;   float M = -1e30f;
; #pragma unroll
;   for (int sidx = 0; sidx < 8; ++sidx) M = fmaxf(M, ph[(sidx * 16 + r) * 132 + 128]);
;   float l = 0.f, acc[8];
; #pragma unroll
;   for (int i = 0; i < 8; ++i) acc[i] = 0.f;
; #pragma unroll
;   for (int sidx = 0; sidx < 8; ++sidx) { const float* pp = ph + (sidx * 16 + r) * 132; const float w = exp2f((pp[128] - M) * C); l += pp[129] * w;
;     const f32x4 a = *(const f32x4*)(pp + col0), b = *(const f32x4*)(pp + col0 + 4);
;     acc[0] += a.x * w; acc[1] += a.y * w; acc[2] += a.z * w; acc[3] += a.w * w; acc[4] += b.x * w; acc[5] += b.y * w; acc[6] += b.z * w; acc[7] += b.w * w; }
;   const float il = 1.f / l;
; #pragma unroll
;   for (int i = 0; i < 8; ++i) out[i] = acc[i] * il;
; }
; __device__ __forceinline__ void phase_post3(const Params& p, int layer, float lambda_init, const int wave_s) {
;     ...
;       for (int i = 0; i < 8; ++i) x[i] = x[i] * rs * sub[a * 8 + i] * post * silu(g[i]);
;       *(u32x4*)(Y + (size_t)r * DM + h * 128 + a * 8) = pack8(x);
;       meta_combine8(PART + (size_t)((4 + h) * 8 * 16) * 132, r, a * 8, 1.f, x1);
	v_add_f32_e32 v18, v18, v19
	v_fmamk_f32 v18, v18, 0x3c000000, v170
	v_cmp_gt_f32_e32 vcc, s94, v18
	v_mul_f32_e32 v19, 0x4b800000, v18
	s_nop 0
	v_cndmask_b32_e32 v18, v18, v19, vcc
	v_rsq_f32_e32 v18, v18
	s_nop 0
	v_mul_f32_e32 v19, 0x45800000, v18
	v_cndmask_b32_e32 v18, v18, v19, vcc
	v_pk_mul_f32 v[10:11], v[10:11], v[18:19] op_sel_hi:[1,0]
	v_pk_mul_f32 v[12:13], v[12:13], v[18:19] op_sel_hi:[1,0]
	v_pk_mul_f32 v[6:7], v[6:7], v[10:11]
	v_mov_b32_e32 v10, v0
	v_pk_mul_f32 v[6:7], v[64:65], v[6:7]
	v_mov_b32_e32 v11, v2
	v_pk_mul_f32 v[4:5], v[4:5], v[6:7]
	v_pk_mul_f32 v[6:7], v[16:17], v[18:19] op_sel_hi:[1,0]
	v_mov_b32_e32 v2, v1
	v_pk_mul_f32 v[6:7], v[10:11], v[6:7]
	v_pk_mul_f32 v[12:13], v[20:21], v[12:13]
	v_pk_mul_f32 v[6:7], v[64:65], v[6:7]
	v_pk_mul_f32 v[12:13], v[64:65], v[12:13]
	v_pk_mul_f32 v[6:7], v[8:9], v[6:7]
	v_pk_mul_f32 v[8:9], v[14:15], v[18:19] op_sel_hi:[1,0]
	v_pk_mul_f32 v[12:13], v[22:23], v[12:13]
	v_pk_mul_f32 v[0:1], v[2:3], v[8:9]
	v_bfe_u32 v8, v5, 16, 1
	v_pk_mul_f32 v[0:1], v[64:65], v[0:1]
	v_bfe_u32 v9, v4, 16, 1
	v_pk_mul_f32 v[0:1], v[28:29], v[0:1]
	v_add3_u32 v4, v4, v9, s15
	v_bfe_u32 v2, v1, 16, 1
	v_bfe_u32 v3, v0, 16, 1
	v_add3_u32 v5, v5, v8, s15
	v_add3_u32 v0, v0, v3, s15
	v_add3_u32 v1, v1, v2, s15
	v_bfe_u32 v2, v12, 16, 1
	v_bfe_u32 v3, v13, 16, 1
	v_bfe_u32 v8, v6, 16, 1
	v_bfe_u32 v9, v7, 16, 1
	v_add3_u32 v7, v7, v9, s15
	v_add3_u32 v6, v6, v8, s15
	v_add3_u32 v3, v13, v3, s15
	v_add3_u32 v2, v12, v2, s15
	v_lshrrev_b32_e32 v8, 16, v2
	v_lshrrev_b32_e32 v9, 16, v3
	v_lshrrev_b32_e32 v2, 16, v6
	v_lshrrev_b32_e32 v3, 16, v7
	v_and_or_b32 v3, v1, s14, v3
	v_and_or_b32 v2, v0, s14, v2
	v_and_or_b32 v1, v5, s14, v9
	v_and_or_b32 v0, v4, s14, v8
	v_lshl_add_u64 v[6:7], v[74:75], 0, s[38:39]
	global_store_dwordx4 v[90:91], v[0:3], off offset:-1024
	v_lshl_add_u64 v[34:35], v[6:7], 0, s[18:19]
	global_load_dwordx2 v[32:33], v[6:7], off offset:512
	global_load_dwordx2 v[36:37], v[34:35], off offset:512
	v_lshl_add_u64 v[40:41], v[6:7], 0, s[6:7]
	v_lshl_add_u64 v[2:3], v[6:7], 0, s[24:25]
	v_lshl_add_u64 v[8:9], v[6:7], 0, s[40:41]
	global_load_dwordx2 v[42:43], v[40:41], off offset:512
	v_lshl_add_u64 v[0:1], v[6:7], 0, s[26:27]
	global_load_dwordx2 v[14:15], v[8:9], off offset:512
	global_load_dwordx2 v[44:45], v[2:3], off offset:512
	global_load_dwordx2 v[10:11], v[0:1], off offset:512
	v_lshl_add_u64 v[12:13], v[6:7], 0, s[42:43]
	v_lshl_add_u64 v[16:17], v[6:7], 0, s[44:45]
	global_load_dwordx2 v[18:19], v[12:13], off offset:512
	global_load_dwordx2 v[20:21], v[16:17], off offset:512
	v_lshl_add_u64 v[6:7], v[6:7], 0, v[88:89]
	global_load_dwordx4 v[24:27], v[6:7], off offset:16
	global_load_dwordx4 v[28:31], v[6:7], off
	v_lshl_add_u64 v[40:41], v[40:41], 0, v[88:89]
	v_lshl_add_u64 v[2:3], v[2:3], 0, v[88:89]
	s_waitcnt vmcnt(8)
	v_max3_f32 v4, v32, s2, v36
	s_waitcnt vmcnt(5)
	v_max3_f32 v4, v4, v42, v44
	s_waitcnt vmcnt(4)
	v_max3_f32 v4, v4, v10, v14
	s_waitcnt vmcnt(2)
	v_max3_f32 v22, v4, v18, v20
	v_sub_f32_e32 v4, v32, v22
	v_cmp_gt_f32_e32 vcc, s12, v4
	s_nop 1
	v_cndmask_b32_e32 v5, 0, v210, vcc
	v_add_f32_e32 v4, v4, v5
	v_exp_f32_e32 v4, v4
	v_cndmask_b32_e32 v5, 0, v211, vcc
	v_ldexp_f32 v4, v4, v5
	v_sub_f32_e32 v5, v36, v22
	v_cmp_gt_f32_e32 vcc, s12, v5
	v_mov_b32_e32 v36, v33
	s_nop 0
	v_cndmask_b32_e32 v6, 0, v210, vcc
	v_add_f32_e32 v5, v5, v6
	v_exp_f32_e32 v5, v5
	v_cndmask_b32_e32 v6, 0, v211, vcc
	v_ldexp_f32 v5, v5, v6
	v_pk_mul_f32 v[6:7], v[36:37], v[4:5]
	s_nop 0
	v_add_f32_e32 v6, 0, v6
	v_add_f32_e32 v23, v6, v7
	v_lshl_add_u64 v[6:7], v[34:35], 0, v[88:89]
	global_load_dwordx4 v[32:35], v[6:7], off offset:16
	global_load_dwordx4 v[36:39], v[6:7], off
	global_load_dwordx4 v[46:49], v[40:41], off offset:16
	global_load_dwordx4 v[50:53], v[40:41], off
	global_load_dwordx4 v[54:57], v[2:3], off offset:16
	global_load_dwordx4 v[58:61], v[2:3], off
	v_sub_f32_e32 v6, v42, v22
	v_cmp_gt_f32_e32 vcc, s12, v6
	s_waitcnt vmcnt(6)
	v_mov_b32_e32 v2, v28
	v_mov_b32_e32 v3, v30
	v_cndmask_b32_e32 v7, 0, v210, vcc
	v_add_f32_e32 v6, v6, v7
	v_exp_f32_e32 v6, v6
	v_cndmask_b32_e32 v7, 0, v211, vcc
	v_pk_fma_f32 v[2:3], v[4:5], v[2:3], 0 op_sel_hi:[0,1,0]
	v_mov_b32_e32 v28, v5
	v_ldexp_f32 v6, v6, v7
	v_sub_f32_e32 v7, v44, v22
	v_cmp_gt_f32_e32 vcc, s12, v7
	v_mov_b32_e32 v44, v43
	v_mov_b32_e32 v30, v29
	v_cndmask_b32_e32 v40, 0, v210, vcc
	v_add_f32_e32 v7, v7, v40
	v_exp_f32_e32 v7, v7
	v_cndmask_b32_e32 v40, 0, v211, vcc
	v_ldexp_f32 v7, v7, v40
	v_pk_mul_f32 v[40:41], v[6:7], v[44:45]
	s_waitcnt vmcnt(0)
	v_mov_b32_e32 v42, v58
	v_add_f32_e32 v23, v23, v40
	v_add_f32_e32 v23, v23, v41
	v_mov_b32_e32 v40, v36
	v_mov_b32_e32 v41, v38
	v_pk_fma_f32 v[2:3], v[28:29], v[40:41], v[2:3] op_sel_hi:[0,1,1]
	v_mov_b32_e32 v40, v50
	v_mov_b32_e32 v41, v52
	v_pk_fma_f32 v[2:3], v[6:7], v[40:41], v[2:3] op_sel_hi:[0,1,1]
	v_mov_b32_e32 v40, v7
	v_mov_b32_e32 v43, v60
	v_pk_fma_f32 v[42:43], v[40:41], v[42:43], v[2:3] op_sel_hi:[0,1,1]
	v_pk_fma_f32 v[2:3], v[4:5], v[30:31], 0 op_sel_hi:[0,1,0]
	v_mov_b32_e32 v38, v37
	v_pk_fma_f32 v[2:3], v[28:29], v[38:39], v[2:3] op_sel_hi:[0,1,1]
	v_mov_b32_e32 v52, v51
	v_pk_fma_f32 v[2:3], v[6:7], v[52:53], v[2:3] op_sel_hi:[0,1,1]
	v_mov_b32_e32 v60, v59
	v_pk_fma_f32 v[44:45], v[40:41], v[60:61], v[2:3] op_sel_hi:[0,1,1]
	v_mov_b32_e32 v2, v24
	v_mov_b32_e32 v3, v26
	v_pk_fma_f32 v[2:3], v[4:5], v[2:3], 0 op_sel_hi:[0,1,0]
	v_mov_b32_e32 v30, v32
	v_mov_b32_e32 v31, v34
	v_pk_fma_f32 v[2:3], v[28:29], v[30:31], v[2:3] op_sel_hi:[0,1,1]
	v_mov_b32_e32 v30, v46
	v_mov_b32_e32 v31, v48
	v_pk_fma_f32 v[2:3], v[6:7], v[30:31], v[2:3] op_sel_hi:[0,1,1]
	v_mov_b32_e32 v30, v54
	v_mov_b32_e32 v31, v56
	v_mov_b32_e32 v26, v25
	v_pk_fma_f32 v[36:37], v[40:41], v[30:31], v[2:3] op_sel_hi:[0,1,1]
	v_pk_fma_f32 v[2:3], v[4:5], v[26:27], 0 op_sel_hi:[0,1,0]
	v_mov_b32_e32 v34, v33
	v_pk_fma_f32 v[2:3], v[28:29], v[34:35], v[2:3] op_sel_hi:[0,1,1]
	v_mov_b32_e32 v48, v47
	v_pk_fma_f32 v[2:3], v[6:7], v[48:49], v[2:3] op_sel_hi:[0,1,1]
	v_mov_b32_e32 v56, v55
	v_pk_fma_f32 v[38:39], v[40:41], v[56:57], v[2:3] op_sel_hi:[0,1,1]
	v_sub_f32_e32 v2, v10, v22
	v_cmp_gt_f32_e32 vcc, s12, v2
	v_lshl_add_u64 v[4:5], v[0:1], 0, v[88:89]
	v_lshl_add_u64 v[28:29], v[12:13], 0, v[88:89]
	v_cndmask_b32_e32 v3, 0, v210, vcc
	v_add_f32_e32 v2, v2, v3
	v_exp_f32_e32 v2, v2
	v_cndmask_b32_e32 v3, 0, v211, vcc
	v_ldexp_f32 v40, v2, v3
	global_load_dwordx4 v[0:3], v[4:5], off offset:16
	s_nop 0
	global_load_dwordx4 v[4:7], v[4:5], off
	s_waitcnt vmcnt(0)
; __device__ __forceinline__ float silu(float g) { return g / (1.f + __expf(-g)); }
; __device__ __forceinline__ void unpack8(const u32x4 w, float* x) { x[0] = bflo(w.x); x[1] = bfhi(w.x); x[2] = bflo(w.y); x[3] = bfhi(w.y); x[4] = bflo(w.z); x[5] = bfhi(w.z); x[6] = bflo(w.w); x[7] = bfhi(w.w); }
; __device__ __forceinline__ u32x4 pack8(const float* x) { u32x4 w; w.x = pk2(x[0], x[1]); w.y = pk2(x[2], x[3]); w.z = pk2(x[4], x[5]); w.w = pk2(x[6], x[7]); return w; }
; __device__ __forceinline__ void meta_combine8(const float* __restrict__ ph, int r, int col0, float C, float* out) {
;   float M = -1e30f;
; #pragma unroll
;   for (int sidx = 0; sidx < 8; ++sidx) M = fmaxf(M, ph[(sidx * 16 + r) * 132 + 128]);
;   float l = 0.f, acc[8];
; #pragma unroll
;   for (int i = 0; i < 8; ++i) acc[i] = 0.f;
; #pragma unroll
;   for (int sidx = 0; sidx < 8; ++sidx) { const float* pp = ph + (sidx * 16 + r) * 132; const float w = exp2f((pp[128] - M) * C); l += pp[129] * w;
;     const f32x4 a = *(const f32x4*)(pp + col0), b = *(const f32x4*)(pp + col0 + 4);
;     acc[0] += a.x * w; acc[1] += a.y * w; acc[2] += a.z * w; acc[3] += a.w * w; acc[4] += b.x * w; acc[5] += b.y * w; acc[6] += b.z * w; acc[7] += b.w * w; }
;   const float il = 1.f / l;
; #pragma unroll
;   for (int i = 0; i < 8; ++i) out[i] = acc[i] * il;
; }
; __device__ __forceinline__ void phase_post3(const Params& p, int layer, float lambda_init, const int wave_s) {
;     ...
;       meta_combine8(PART + (size_t)((4 + h) * 8 * 16) * 132, r, a * 8, 1.f, x1);
;       unpack8(*(const u32x4*)(P + (size_t)r * INP + C_BG + h * 128 + a * 8), g);
; #pragma unroll
;       for (int i = 0; i < 8; ++i) x1[i] *= silu(g[i]);
;       *(u32x4*)(Y + (size_t)r * DM + 512 + h * 128 + a * 8) = pack8(x1);
	v_mov_b32_e32 v46, v4
	v_mov_b32_e32 v4, v0
	v_sub_f32_e32 v0, v14, v22
	v_cmp_gt_f32_e32 vcc, s12, v0
	v_mov_b32_e32 v47, v6
	v_mov_b32_e32 v6, v5
	v_mov_b32_e32 v5, v2
	v_mov_b32_e32 v2, v1
	v_cndmask_b32_e32 v1, 0, v210, vcc
	v_add_f32_e32 v0, v0, v1
	v_exp_f32_e32 v0, v0
	v_cndmask_b32_e32 v1, 0, v211, vcc
	v_mov_b32_e32 v14, v11
	v_ldexp_f32 v41, v0, v1
	v_pk_mul_f32 v[0:1], v[40:41], v[14:15]
	v_pk_fma_f32 v[46:47], v[40:41], v[46:47], v[42:43] op_sel_hi:[0,1,1]
	v_add_f32_e32 v0, v23, v0
	v_add_f32_e32 v23, v0, v1
	v_lshl_add_u64 v[0:1], v[8:9], 0, v[88:89]
	global_load_dwordx4 v[8:11], v[0:1], off offset:16
	global_load_dwordx4 v[24:27], v[0:1], off
	v_sub_f32_e32 v0, v18, v22
	v_cmp_gt_f32_e32 vcc, s12, v0
	global_load_dwordx4 v[12:15], v[28:29], off offset:16
	s_nop 0
	global_load_dwordx4 v[28:31], v[28:29], off
	v_cndmask_b32_e32 v1, 0, v210, vcc
	v_add_f32_e32 v0, v0, v1
	v_exp_f32_e32 v0, v0
	v_cndmask_b32_e32 v1, 0, v211, vcc
	v_pk_fma_f32 v[6:7], v[40:41], v[6:7], v[44:45] op_sel_hi:[0,1,1]
	v_mov_b32_e32 v42, v41
	v_ldexp_f32 v0, v0, v1
	v_sub_f32_e32 v1, v20, v22
	v_cmp_gt_f32_e32 vcc, s12, v1
	v_mov_b32_e32 v20, v19
	v_pk_fma_f32 v[4:5], v[40:41], v[4:5], v[36:37] op_sel_hi:[0,1,1]
	v_cndmask_b32_e32 v18, 0, v210, vcc
	v_add_f32_e32 v1, v1, v18
	v_exp_f32_e32 v1, v1
	v_cndmask_b32_e32 v18, 0, v211, vcc
	v_pk_fma_f32 v[2:3], v[40:41], v[2:3], v[38:39] op_sel_hi:[0,1,1]
	v_ldexp_f32 v1, v1, v18
	v_pk_mul_f32 v[18:19], v[0:1], v[20:21]
	v_lshl_add_u64 v[20:21], v[16:17], 0, v[88:89]
	v_add_f32_e32 v18, v23, v18
	v_add_f32_e32 v22, v18, v19
	global_load_dwordx4 v[16:19], v[20:21], off offset:16
	global_load_dwordx4 v[32:35], v[20:21], off
	v_div_scale_f32 v20, s[0:1], v22, v22, 1.0
	v_rcp_f32_e32 v21, v20
	s_mov_b32 s0, 0x8421000
	v_fma_f32 v23, -v20, v21, 1.0
	v_fmac_f32_e32 v21, v23, v21
	v_div_scale_f32 v23, vcc, 1.0, v22, 1.0
	v_mul_f32_e32 v48, v23, v21
	v_fma_f32 v49, -v20, v48, v23
	v_fmac_f32_e32 v48, v49, v21
	v_fma_f32 v20, -v20, v48, v23
	v_div_fmas_f32 v20, v20, v21, v48
	v_div_fixup_f32 v48, v20, v22, 1.0
	v_add_co_u32_e32 v20, vcc, s0, v92
	s_waitcnt vmcnt(4)
	v_mov_b32_e32 v44, v24
	v_addc_co_u32_e32 v21, vcc, 0, v93, vcc
	global_load_dwordx4 v[20:23], v[20:21], off offset:2048
	v_mov_b32_e32 v45, v26
	v_mov_b32_e32 v26, v25
	v_pk_fma_f32 v[44:45], v[42:43], v[44:45], v[46:47] op_sel_hi:[0,1,1]
	v_pk_fma_f32 v[6:7], v[42:43], v[26:27], v[6:7] op_sel_hi:[0,1,1]
	s_waitcnt vmcnt(3)
	v_mov_b32_e32 v24, v28
	v_mov_b32_e32 v25, v30
	v_mov_b32_e32 v30, v29
	v_pk_fma_f32 v[26:27], v[0:1], v[24:25], v[44:45] op_sel_hi:[0,1,1]
	v_pk_fma_f32 v[6:7], v[0:1], v[30:31], v[6:7] op_sel_hi:[0,1,1]
	v_mov_b32_e32 v24, v1
	s_waitcnt vmcnt(1)
	v_mov_b32_e32 v29, v34
	v_mov_b32_e32 v34, v33
	v_mov_b32_e32 v28, v32
	v_pk_fma_f32 v[6:7], v[24:25], v[34:35], v[6:7] op_sel_hi:[0,1,1]
	v_pk_fma_f32 v[26:27], v[24:25], v[28:29], v[26:27] op_sel_hi:[0,1,1]
	v_pk_mul_f32 v[28:29], v[48:49], v[6:7] op_sel_hi:[0,1]
	v_pk_mul_f32 v[26:27], v[48:49], v[26:27] op_sel_hi:[0,1]
	s_waitcnt vmcnt(0)
	v_and_b32_e32 v31, 0xffff0000, v20
	v_lshlrev_b32_e32 v1, 16, v21
	v_lshlrev_b32_e32 v25, 16, v20
	v_mul_f32_e32 v7, 0xbfb8aa3b, v31
	v_mul_f32_e32 v6, 0xbfb8aa3b, v25
	v_exp_f32_e32 v20, v7
	v_mul_f32_e32 v7, 0xbfb8aa3b, v1
	v_exp_f32_e32 v6, v6
	v_exp_f32_e32 v7, v7
	v_and_b32_e32 v30, 0xffff0000, v21
	v_pk_add_f32 v[6:7], v[6:7], 1.0 op_sel_hi:[1,0]
	s_nop 0
	v_div_scale_f32 v21, s[0:1], v7, v7, v1
	v_rcp_f32_e32 v32, v21
	s_nop 0
	v_fma_f32 v33, -v21, v32, 1.0
	v_fmac_f32_e32 v32, v33, v32
	v_div_scale_f32 v33, vcc, v1, v7, v1
	v_mul_f32_e32 v34, v33, v32
	v_fma_f32 v35, -v21, v34, v33
	v_fmac_f32_e32 v34, v35, v32
	v_fma_f32 v21, -v21, v34, v33
	v_div_fmas_f32 v21, v21, v32, v34
	v_div_fixup_f32 v7, v21, v7, v1
	v_div_scale_f32 v1, s[0:1], v6, v6, v25
	v_rcp_f32_e32 v21, v1
	s_nop 0
	v_fma_f32 v32, -v1, v21, 1.0
	v_fmac_f32_e32 v21, v32, v21
	v_div_scale_f32 v32, vcc, v25, v6, v25
	v_mul_f32_e32 v33, v32, v21
	v_fma_f32 v34, -v1, v33, v32
	v_fmac_f32_e32 v33, v34, v21
	v_fma_f32 v1, -v1, v33, v32
	v_div_fmas_f32 v1, v1, v21, v33
	v_div_fixup_f32 v6, v1, v6, v25
	v_mul_f32_e32 v1, 0xbfb8aa3b, v30
	v_exp_f32_e32 v21, v1
	v_pk_mul_f32 v[6:7], v[26:27], v[6:7]
	v_pk_add_f32 v[20:21], v[20:21], 1.0 op_sel_hi:[1,0]
	s_nop 0
	v_div_scale_f32 v1, s[0:1], v21, v21, v30
	v_rcp_f32_e32 v25, v1
	s_nop 0
	v_fma_f32 v26, -v1, v25, 1.0
	v_fmac_f32_e32 v25, v26, v25
	v_div_scale_f32 v26, vcc, v30, v21, v30
	v_mul_f32_e32 v27, v26, v25
	v_fma_f32 v32, -v1, v27, v26
	v_fmac_f32_e32 v27, v32, v25
	v_fma_f32 v1, -v1, v27, v26
	v_div_fmas_f32 v1, v1, v25, v27
	v_div_fixup_f32 v21, v1, v21, v30
	v_div_scale_f32 v1, s[0:1], v20, v20, v31
	v_rcp_f32_e32 v25, v1
	s_nop 0
	v_fma_f32 v26, -v1, v25, 1.0
	v_fmac_f32_e32 v25, v26, v25
	v_div_scale_f32 v26, vcc, v31, v20, v31
	v_mul_f32_e32 v27, v26, v25
	v_fma_f32 v30, -v1, v27, v26
	v_fmac_f32_e32 v27, v30, v25
	v_fma_f32 v1, -v1, v27, v26
	v_div_fmas_f32 v1, v1, v25, v27
	v_mov_b32_e32 v26, v8
	v_mov_b32_e32 v27, v10
	v_mov_b32_e32 v10, v9
	v_pk_fma_f32 v[4:5], v[42:43], v[26:27], v[4:5] op_sel_hi:[0,1,1]
	v_pk_fma_f32 v[2:3], v[42:43], v[10:11], v[2:3] op_sel_hi:[0,1,1]
	v_mov_b32_e32 v8, v12
	v_mov_b32_e32 v9, v14
	v_mov_b32_e32 v14, v13
	v_div_fixup_f32 v20, v1, v20, v31
	v_pk_fma_f32 v[4:5], v[0:1], v[8:9], v[4:5] op_sel_hi:[0,1,1]
	v_pk_fma_f32 v[0:1], v[0:1], v[14:15], v[2:3] op_sel_hi:[0,1,1]
	v_mov_b32_e32 v2, v16
	v_mov_b32_e32 v3, v18
	v_and_b32_e32 v12, 0xffff0000, v22
	v_pk_fma_f32 v[2:3], v[24:25], v[2:3], v[4:5] op_sel_hi:[0,1,1]
	v_lshlrev_b32_e32 v9, 16, v23
	v_lshlrev_b32_e32 v10, 16, v22
; __device__ __forceinline__ float silu(float g) { return g / (1.f + __expf(-g)); }
; __device__ __forceinline__ u32x4 pack8(const float* x) { u32x4 w; w.x = pk2(x[0], x[1]); w.y = pk2(x[2], x[3]); w.z = pk2(x[4], x[5]); w.w = pk2(x[6], x[7]); return w; }
; __device__ __forceinline__ void meta_combine8(const float* __restrict__ ph, int r, int col0, float C, float* out) {
;   float M = -1e30f;
; #pragma unroll
;   for (int sidx = 0; sidx < 8; ++sidx) M = fmaxf(M, ph[(sidx * 16 + r) * 132 + 128]);
;   float l = 0.f, acc[8];
; #pragma unroll
;   for (int i = 0; i < 8; ++i) acc[i] = 0.f;
; #pragma unroll
;   for (int sidx = 0; sidx < 8; ++sidx) { const float* pp = ph + (sidx * 16 + r) * 132; const float w = exp2f((pp[128] - M) * C); l += pp[129] * w;
;     const f32x4 a = *(const f32x4*)(pp + col0), b = *(const f32x4*)(pp + col0 + 4);
;     acc[0] += a.x * w; acc[1] += a.y * w; acc[2] += a.z * w; acc[3] += a.w * w; acc[4] += b.x * w; acc[5] += b.y * w; acc[6] += b.z * w; acc[7] += b.w * w; }
;   const float il = 1.f / l;
; #pragma unroll
;   for (int i = 0; i < 8; ++i) out[i] = acc[i] * il;
; }
; __device__ __forceinline__ void phase_post3(const Params& p, int layer, float lambda_init, const int wave_s) {
;     ...
;       for (int i = 0; i < 8; ++i) x1[i] *= silu(g[i]);
;       *(u32x4*)(Y + (size_t)r * DM + 512 + h * 128 + a * 8) = pack8(x1);
;       meta_combine8(PART + (size_t)(h * 8 * 16) * 132, r, a * 8, 1.f, x2);
	v_mul_f32_e32 v5, 0xbfb8aa3b, v12
	v_mul_f32_e32 v4, 0xbfb8aa3b, v10
	v_exp_f32_e32 v8, v5
	v_mul_f32_e32 v5, 0xbfb8aa3b, v9
	v_exp_f32_e32 v4, v4
	v_exp_f32_e32 v5, v5
	v_mov_b32_e32 v18, v17
	v_pk_mul_f32 v[2:3], v[48:49], v[2:3] op_sel_hi:[0,1]
	v_and_b32_e32 v11, 0xffff0000, v23
	v_pk_add_f32 v[4:5], v[4:5], 1.0 op_sel_hi:[1,0]
	v_pk_fma_f32 v[0:1], v[24:25], v[18:19], v[0:1] op_sel_hi:[0,1,1]
	v_div_scale_f32 v13, s[0:1], v5, v5, v9
	v_rcp_f32_e32 v14, v13
	v_pk_mul_f32 v[0:1], v[48:49], v[0:1] op_sel_hi:[0,1]
	v_pk_mul_f32 v[20:21], v[28:29], v[20:21]
	v_fma_f32 v15, -v13, v14, 1.0
	v_fmac_f32_e32 v14, v15, v14
	v_div_scale_f32 v15, vcc, v9, v5, v9
	v_mul_f32_e32 v16, v15, v14
	v_fma_f32 v17, -v13, v16, v15
	v_fmac_f32_e32 v16, v17, v14
	v_fma_f32 v13, -v13, v16, v15
	v_div_fmas_f32 v13, v13, v14, v16
	v_div_fixup_f32 v5, v13, v5, v9
	v_div_scale_f32 v9, s[0:1], v4, v4, v10
	v_rcp_f32_e32 v13, v9
	s_nop 0
	v_fma_f32 v14, -v9, v13, 1.0
	v_fmac_f32_e32 v13, v14, v13
	v_div_scale_f32 v14, vcc, v10, v4, v10
	v_mul_f32_e32 v15, v14, v13
	v_fma_f32 v16, -v9, v15, v14
	v_fmac_f32_e32 v15, v16, v13
	v_fma_f32 v9, -v9, v15, v14
	v_div_fmas_f32 v9, v9, v13, v15
	v_div_fixup_f32 v4, v9, v4, v10
	v_pk_mul_f32 v[2:3], v[2:3], v[4:5]
	v_mul_f32_e32 v4, 0xbfb8aa3b, v11
	v_exp_f32_e32 v9, v4
	s_nop 0
	v_pk_add_f32 v[4:5], v[8:9], 1.0 op_sel_hi:[1,0]
	s_nop 0
	v_div_scale_f32 v8, s[0:1], v5, v5, v11
	v_rcp_f32_e32 v9, v8
	s_nop 0
	v_fma_f32 v10, -v8, v9, 1.0
	v_fmac_f32_e32 v9, v10, v9
	v_div_scale_f32 v10, vcc, v11, v5, v11
	v_mul_f32_e32 v13, v10, v9
	v_fma_f32 v14, -v8, v13, v10
	v_fmac_f32_e32 v13, v14, v9
	v_fma_f32 v8, -v8, v13, v10
	v_div_fmas_f32 v8, v8, v9, v13
	v_div_fixup_f32 v5, v8, v5, v11
	v_div_scale_f32 v8, s[0:1], v4, v4, v12
	v_rcp_f32_e32 v9, v8
	s_nop 0
	v_fma_f32 v10, -v8, v9, 1.0
	v_fmac_f32_e32 v9, v10, v9
	v_div_scale_f32 v10, vcc, v12, v4, v12
	v_mul_f32_e32 v11, v10, v9
	v_fma_f32 v13, -v8, v11, v10
	v_fmac_f32_e32 v11, v13, v9
	v_fma_f32 v8, -v8, v11, v10
	v_div_fmas_f32 v8, v8, v9, v11
	v_div_fixup_f32 v4, v8, v4, v12
	v_pk_mul_f32 v[0:1], v[0:1], v[4:5]
	v_bfe_u32 v10, v2, 16, 1
	v_bfe_u32 v4, v1, 16, 1
	v_bfe_u32 v5, v0, 16, 1
	v_add3_u32 v0, v0, v5, s15
	v_add3_u32 v1, v1, v4, s15
	v_bfe_u32 v4, v6, 16, 1
	v_bfe_u32 v5, v7, 16, 1
	v_bfe_u32 v11, v3, 16, 1
	v_bfe_u32 v8, v21, 16, 1
	v_bfe_u32 v9, v20, 16, 1
	v_add3_u32 v3, v3, v11, s15
	v_add3_u32 v2, v2, v10, s15
	v_add3_u32 v5, v7, v5, s15
	v_add3_u32 v4, v6, v4, s15
	v_add3_u32 v9, v20, v9, s15
	v_add3_u32 v8, v21, v8, s15
	v_lshrrev_b32_e32 v4, 16, v4
	v_lshrrev_b32_e32 v5, 16, v5
	v_lshrrev_b32_e32 v2, 16, v2
	v_lshrrev_b32_e32 v3, 16, v3
	v_and_or_b32 v3, v1, s14, v3
	v_and_or_b32 v2, v0, s14, v2
	v_and_or_b32 v1, v8, s14, v5
	v_and_or_b32 v0, v9, s14, v4
	v_lshl_add_u64 v[6:7], v[72:73], 0, s[38:39]
	global_store_dwordx4 v[90:91], v[0:3], off
	v_lshl_add_u64 v[34:35], v[6:7], 0, s[18:19]
	global_load_dwordx2 v[32:33], v[6:7], off offset:512
	global_load_dwordx2 v[36:37], v[34:35], off offset:512
	v_lshl_add_u64 v[40:41], v[6:7], 0, s[6:7]
	v_lshl_add_u64 v[2:3], v[6:7], 0, s[24:25]
	v_lshl_add_u64 v[8:9], v[6:7], 0, s[40:41]
	global_load_dwordx2 v[42:43], v[40:41], off offset:512
	v_lshl_add_u64 v[0:1], v[6:7], 0, s[26:27]
	global_load_dwordx2 v[14:15], v[8:9], off offset:512
	global_load_dwordx2 v[44:45], v[2:3], off offset:512
	global_load_dwordx2 v[10:11], v[0:1], off offset:512
	v_lshl_add_u64 v[12:13], v[6:7], 0, s[42:43]
	v_lshl_add_u64 v[16:17], v[6:7], 0, s[44:45]
	global_load_dwordx2 v[18:19], v[12:13], off offset:512
	global_load_dwordx2 v[20:21], v[16:17], off offset:512
	v_lshl_add_u64 v[6:7], v[6:7], 0, v[88:89]
	global_load_dwordx4 v[24:27], v[6:7], off offset:16
	global_load_dwordx4 v[28:31], v[6:7], off
	v_lshl_add_u64 v[40:41], v[40:41], 0, v[88:89]
	v_lshl_add_u64 v[2:3], v[2:3], 0, v[88:89]
	s_mov_b64 s[38:39], s[34:35]
	s_waitcnt vmcnt(8)
	v_max3_f32 v4, v32, s2, v36
	s_waitcnt vmcnt(5)
	v_max3_f32 v4, v4, v42, v44
	s_waitcnt vmcnt(4)
	v_max3_f32 v4, v4, v10, v14
	s_waitcnt vmcnt(2)
	v_max3_f32 v22, v4, v18, v20
	v_sub_f32_e32 v4, v32, v22
	v_cmp_gt_f32_e32 vcc, s12, v4
	s_nop 1
	v_cndmask_b32_e32 v5, 0, v210, vcc
	v_add_f32_e32 v4, v4, v5
	v_exp_f32_e32 v4, v4
	v_cndmask_b32_e32 v5, 0, v211, vcc
	v_ldexp_f32 v4, v4, v5
	v_sub_f32_e32 v5, v36, v22
	v_cmp_gt_f32_e32 vcc, s12, v5
	v_mov_b32_e32 v36, v33
	s_nop 0
	v_cndmask_b32_e32 v6, 0, v210, vcc
	v_add_f32_e32 v5, v5, v6
	v_exp_f32_e32 v5, v5
	v_cndmask_b32_e32 v6, 0, v211, vcc
	v_ldexp_f32 v5, v5, v6
	v_pk_mul_f32 v[6:7], v[36:37], v[4:5]
	s_nop 0
	v_add_f32_e32 v6, 0, v6
	v_add_f32_e32 v23, v6, v7
	v_lshl_add_u64 v[6:7], v[34:35], 0, v[88:89]
	global_load_dwordx4 v[32:35], v[6:7], off offset:16
	global_load_dwordx4 v[36:39], v[6:7], off
	global_load_dwordx4 v[46:49], v[40:41], off offset:16
	global_load_dwordx4 v[50:53], v[40:41], off
	global_load_dwordx4 v[54:57], v[2:3], off offset:16
	global_load_dwordx4 v[58:61], v[2:3], off
	v_sub_f32_e32 v6, v42, v22
	v_cmp_gt_f32_e32 vcc, s12, v6
	s_waitcnt vmcnt(6)
	v_mov_b32_e32 v2, v28
	v_mov_b32_e32 v3, v30
	v_cndmask_b32_e32 v7, 0, v210, vcc
	v_add_f32_e32 v6, v6, v7
	v_exp_f32_e32 v6, v6
	v_cndmask_b32_e32 v7, 0, v211, vcc
	v_pk_fma_f32 v[2:3], v[4:5], v[2:3], 0 op_sel_hi:[0,1,0]
	v_mov_b32_e32 v28, v5
	v_ldexp_f32 v6, v6, v7
	v_sub_f32_e32 v7, v44, v22
	v_cmp_gt_f32_e32 vcc, s12, v7
	v_mov_b32_e32 v44, v43
	v_mov_b32_e32 v30, v29
	v_cndmask_b32_e32 v40, 0, v210, vcc
	v_add_f32_e32 v7, v7, v40
	v_exp_f32_e32 v7, v7
	v_cndmask_b32_e32 v40, 0, v211, vcc
	v_ldexp_f32 v7, v7, v40
	v_pk_mul_f32 v[40:41], v[6:7], v[44:45]
	s_waitcnt vmcnt(0)
; __device__ __forceinline__ float silu(float g) { return g / (1.f + __expf(-g)); }
; __device__ __forceinline__ void unpack8(const u32x4 w, float* x) { x[0] = bflo(w.x); x[1] = bfhi(w.x); x[2] = bflo(w.y); x[3] = bfhi(w.y); x[4] = bflo(w.z); x[5] = bfhi(w.z); x[6] = bflo(w.w); x[7] = bfhi(w.w); }
; __device__ __forceinline__ void meta_combine8(const float* __restrict__ ph, int r, int col0, float C, float* out) {
;   float M = -1e30f;
; #pragma unroll
;   for (int sidx = 0; sidx < 8; ++sidx) M = fmaxf(M, ph[(sidx * 16 + r) * 132 + 128]);
;   float l = 0.f, acc[8];
; #pragma unroll
;   for (int i = 0; i < 8; ++i) acc[i] = 0.f;
; #pragma unroll
;   for (int sidx = 0; sidx < 8; ++sidx) { const float* pp = ph + (sidx * 16 + r) * 132; const float w = exp2f((pp[128] - M) * C); l += pp[129] * w;
;     const f32x4 a = *(const f32x4*)(pp + col0), b = *(const f32x4*)(pp + col0 + 4);
;     acc[0] += a.x * w; acc[1] += a.y * w; acc[2] += a.z * w; acc[3] += a.w * w; acc[4] += b.x * w; acc[5] += b.y * w; acc[6] += b.z * w; acc[7] += b.w * w; }
;   const float il = 1.f / l;
; #pragma unroll
;   for (int i = 0; i < 8; ++i) out[i] = acc[i] * il;
; }
; __device__ __forceinline__ void phase_post3(const Params& p, int layer, float lambda_init, const int wave_s) {
;     ...
;       meta_combine8(PART + (size_t)(h * 8 * 16) * 132, r, a * 8, 1.f, x2);
;       unpack8(*(const u32x4*)(P + (size_t)r * INP + C_CG + h * 128 + a * 8), g);
; #pragma unroll
;       for (int i = 0; i < 8; ++i) x2[i] *= silu(g[i]);
	v_mov_b32_e32 v42, v58
	v_add_f32_e32 v23, v23, v40
	v_add_f32_e32 v23, v23, v41
	v_mov_b32_e32 v40, v36
	v_mov_b32_e32 v41, v38
	v_pk_fma_f32 v[2:3], v[28:29], v[40:41], v[2:3] op_sel_hi:[0,1,1]
	v_mov_b32_e32 v40, v50
	v_mov_b32_e32 v41, v52
	v_pk_fma_f32 v[2:3], v[6:7], v[40:41], v[2:3] op_sel_hi:[0,1,1]
	v_mov_b32_e32 v40, v7
	v_mov_b32_e32 v43, v60
	v_pk_fma_f32 v[42:43], v[40:41], v[42:43], v[2:3] op_sel_hi:[0,1,1]
	v_pk_fma_f32 v[2:3], v[4:5], v[30:31], 0 op_sel_hi:[0,1,0]
	v_mov_b32_e32 v38, v37
	v_pk_fma_f32 v[2:3], v[28:29], v[38:39], v[2:3] op_sel_hi:[0,1,1]
	v_mov_b32_e32 v52, v51
	v_pk_fma_f32 v[2:3], v[6:7], v[52:53], v[2:3] op_sel_hi:[0,1,1]
	v_mov_b32_e32 v60, v59
	v_pk_fma_f32 v[44:45], v[40:41], v[60:61], v[2:3] op_sel_hi:[0,1,1]
	v_mov_b32_e32 v2, v24
	v_mov_b32_e32 v3, v26
	v_pk_fma_f32 v[2:3], v[4:5], v[2:3], 0 op_sel_hi:[0,1,0]
	v_mov_b32_e32 v30, v32
	v_mov_b32_e32 v31, v34
	v_pk_fma_f32 v[2:3], v[28:29], v[30:31], v[2:3] op_sel_hi:[0,1,1]
	v_mov_b32_e32 v30, v46
	v_mov_b32_e32 v31, v48
	v_pk_fma_f32 v[2:3], v[6:7], v[30:31], v[2:3] op_sel_hi:[0,1,1]
	v_mov_b32_e32 v30, v54
	v_mov_b32_e32 v31, v56
	v_mov_b32_e32 v26, v25
	v_pk_fma_f32 v[36:37], v[40:41], v[30:31], v[2:3] op_sel_hi:[0,1,1]
	v_pk_fma_f32 v[2:3], v[4:5], v[26:27], 0 op_sel_hi:[0,1,0]
	v_mov_b32_e32 v34, v33
	v_pk_fma_f32 v[2:3], v[28:29], v[34:35], v[2:3] op_sel_hi:[0,1,1]
	v_mov_b32_e32 v48, v47
	v_pk_fma_f32 v[2:3], v[6:7], v[48:49], v[2:3] op_sel_hi:[0,1,1]
	v_mov_b32_e32 v56, v55
	v_pk_fma_f32 v[38:39], v[40:41], v[56:57], v[2:3] op_sel_hi:[0,1,1]
	v_sub_f32_e32 v2, v10, v22
	v_cmp_gt_f32_e32 vcc, s12, v2
	v_lshl_add_u64 v[4:5], v[0:1], 0, v[88:89]
	v_lshl_add_u64 v[28:29], v[12:13], 0, v[88:89]
	v_cndmask_b32_e32 v3, 0, v210, vcc
	v_add_f32_e32 v2, v2, v3
	v_exp_f32_e32 v2, v2
	v_cndmask_b32_e32 v3, 0, v211, vcc
	v_ldexp_f32 v40, v2, v3
	global_load_dwordx4 v[0:3], v[4:5], off offset:16
	s_nop 0
	global_load_dwordx4 v[4:7], v[4:5], off
	s_waitcnt vmcnt(0)
	v_mov_b32_e32 v46, v4
	v_mov_b32_e32 v4, v0
	v_sub_f32_e32 v0, v14, v22
	v_cmp_gt_f32_e32 vcc, s12, v0
	v_mov_b32_e32 v47, v6
	v_mov_b32_e32 v6, v5
	v_mov_b32_e32 v5, v2
	v_mov_b32_e32 v2, v1
	v_cndmask_b32_e32 v1, 0, v210, vcc
	v_add_f32_e32 v0, v0, v1
	v_exp_f32_e32 v0, v0
	v_cndmask_b32_e32 v1, 0, v211, vcc
	v_mov_b32_e32 v14, v11
	v_ldexp_f32 v41, v0, v1
	v_pk_mul_f32 v[0:1], v[40:41], v[14:15]
	v_pk_fma_f32 v[46:47], v[40:41], v[46:47], v[42:43] op_sel_hi:[0,1,1]
	v_add_f32_e32 v0, v23, v0
	v_add_f32_e32 v23, v0, v1
	v_lshl_add_u64 v[0:1], v[8:9], 0, v[88:89]
	global_load_dwordx4 v[8:11], v[0:1], off offset:16
	global_load_dwordx4 v[24:27], v[0:1], off
	v_sub_f32_e32 v0, v18, v22
	v_cmp_gt_f32_e32 vcc, s12, v0
	global_load_dwordx4 v[12:15], v[28:29], off offset:16
	s_nop 0
	global_load_dwordx4 v[28:31], v[28:29], off
	v_cndmask_b32_e32 v1, 0, v210, vcc
	v_add_f32_e32 v0, v0, v1
	v_exp_f32_e32 v0, v0
	v_cndmask_b32_e32 v1, 0, v211, vcc
	v_pk_fma_f32 v[6:7], v[40:41], v[6:7], v[44:45] op_sel_hi:[0,1,1]
	v_mov_b32_e32 v42, v41
	v_ldexp_f32 v0, v0, v1
	v_sub_f32_e32 v1, v20, v22
	v_cmp_gt_f32_e32 vcc, s12, v1
	v_mov_b32_e32 v20, v19
	v_pk_fma_f32 v[4:5], v[40:41], v[4:5], v[36:37] op_sel_hi:[0,1,1]
	v_cndmask_b32_e32 v18, 0, v210, vcc
	v_add_f32_e32 v1, v1, v18
	v_exp_f32_e32 v1, v1
	v_cndmask_b32_e32 v18, 0, v211, vcc
	v_pk_fma_f32 v[2:3], v[40:41], v[2:3], v[38:39] op_sel_hi:[0,1,1]
	v_ldexp_f32 v1, v1, v18
	v_pk_mul_f32 v[18:19], v[0:1], v[20:21]
	v_lshl_add_u64 v[20:21], v[16:17], 0, v[88:89]
	v_add_f32_e32 v18, v23, v18
	v_add_f32_e32 v22, v18, v19
	global_load_dwordx4 v[16:19], v[20:21], off offset:16
	global_load_dwordx4 v[32:35], v[20:21], off
	v_div_scale_f32 v20, s[0:1], v22, v22, 1.0
	v_rcp_f32_e32 v21, v20
	s_mov_b32 s0, 0x8422000
	v_fma_f32 v23, -v20, v21, 1.0
	v_fmac_f32_e32 v21, v23, v21
	v_div_scale_f32 v23, vcc, 1.0, v22, 1.0
	v_mul_f32_e32 v48, v23, v21
	v_fma_f32 v49, -v20, v48, v23
	v_fmac_f32_e32 v48, v49, v21
	v_fma_f32 v20, -v20, v48, v23
	v_div_fmas_f32 v20, v20, v21, v48
	v_div_fixup_f32 v48, v20, v22, 1.0
	v_add_co_u32_e32 v20, vcc, s0, v92
	s_waitcnt vmcnt(4)
	v_mov_b32_e32 v44, v24
	v_addc_co_u32_e32 v21, vcc, 0, v93, vcc
	global_load_dwordx4 v[20:23], v[20:21], off offset:384
	v_mov_b32_e32 v45, v26
	v_mov_b32_e32 v26, v25
	v_pk_fma_f32 v[44:45], v[42:43], v[44:45], v[46:47] op_sel_hi:[0,1,1]
	v_pk_fma_f32 v[6:7], v[42:43], v[26:27], v[6:7] op_sel_hi:[0,1,1]
	s_waitcnt vmcnt(3)
	v_mov_b32_e32 v24, v28
	v_mov_b32_e32 v25, v30
	v_mov_b32_e32 v30, v29
	v_pk_fma_f32 v[26:27], v[0:1], v[24:25], v[44:45] op_sel_hi:[0,1,1]
	v_pk_fma_f32 v[6:7], v[0:1], v[30:31], v[6:7] op_sel_hi:[0,1,1]
	v_mov_b32_e32 v24, v1
	s_waitcnt vmcnt(1)
	v_mov_b32_e32 v29, v34
	v_mov_b32_e32 v34, v33
	v_mov_b32_e32 v28, v32
	v_pk_fma_f32 v[6:7], v[24:25], v[34:35], v[6:7] op_sel_hi:[0,1,1]
	v_pk_fma_f32 v[26:27], v[24:25], v[28:29], v[26:27] op_sel_hi:[0,1,1]
	v_pk_mul_f32 v[28:29], v[48:49], v[6:7] op_sel_hi:[0,1]
	v_pk_mul_f32 v[26:27], v[48:49], v[26:27] op_sel_hi:[0,1]
	s_waitcnt vmcnt(0)
; __device__ __forceinline__ float silu(float g) { return g / (1.f + __expf(-g)); }
; __device__ __forceinline__ void unpack8(const u32x4 w, float* x) { x[0] = bflo(w.x); x[1] = bfhi(w.x); x[2] = bflo(w.y); x[3] = bfhi(w.y); x[4] = bflo(w.z); x[5] = bfhi(w.z); x[6] = bflo(w.w); x[7] = bfhi(w.w); }
; __device__ __forceinline__ u32x4 pack8(const float* x) { u32x4 w; w.x = pk2(x[0], x[1]); w.y = pk2(x[2], x[3]); w.z = pk2(x[4], x[5]); w.w = pk2(x[6], x[7]); return w; }
; __device__ __forceinline__ void meta_combine8(const float* __restrict__ ph, int r, int col0, float C, float* out) {
;     ...
;   for (int sidx = 0; sidx < 8; ++sidx) { const float* pp = ph + (sidx * 16 + r) * 132; const float w = exp2f((pp[128] - M) * C); l += pp[129] * w;
;     const f32x4 a = *(const f32x4*)(pp + col0), b = *(const f32x4*)(pp + col0 + 4);
;     acc[0] += a.x * w; acc[1] += a.y * w; acc[2] += a.z * w; acc[3] += a.w * w; acc[4] += b.x * w; acc[5] += b.y * w; acc[6] += b.z * w; acc[7] += b.w * w; }
;   const float il = 1.f / l;
; #pragma unroll
;   for (int i = 0; i < 8; ++i) out[i] = acc[i] * il;
; __device__ __forceinline__ void phase_post3(const Params& p, int layer, float lambda_init, const int wave_s) {
;     ...
;       meta_combine8(PART + (size_t)((4 + h) * 8 * 16) * 132, r, a * 8, 1.f, x1);
;       unpack8(*(const u32x4*)(P + (size_t)r * INP + C_BG + h * 128 + a * 8), g);
; #pragma unroll
;       for (int i = 0; i < 8; ++i) x1[i] *= silu(g[i]);
;       *(u32x4*)(Y + (size_t)r * DM + 512 + h * 128 + a * 8) = pack8(x1);
	v_and_b32_e32 v31, 0xffff0000, v20
	v_lshlrev_b32_e32 v1, 16, v21
	v_lshlrev_b32_e32 v25, 16, v20
	v_mul_f32_e32 v7, 0xbfb8aa3b, v31
	v_mul_f32_e32 v6, 0xbfb8aa3b, v25
	v_exp_f32_e32 v20, v7
	v_mul_f32_e32 v7, 0xbfb8aa3b, v1
	v_exp_f32_e32 v6, v6
	v_exp_f32_e32 v7, v7
	v_and_b32_e32 v30, 0xffff0000, v21
	v_pk_add_f32 v[6:7], v[6:7], 1.0 op_sel_hi:[1,0]
	s_nop 0
	v_div_scale_f32 v21, s[0:1], v7, v7, v1
	v_rcp_f32_e32 v32, v21
	s_nop 0
	v_fma_f32 v33, -v21, v32, 1.0
	v_fmac_f32_e32 v32, v33, v32
	v_div_scale_f32 v33, vcc, v1, v7, v1
	v_mul_f32_e32 v34, v33, v32
	v_fma_f32 v35, -v21, v34, v33
	v_fmac_f32_e32 v34, v35, v32
	v_fma_f32 v21, -v21, v34, v33
	v_div_fmas_f32 v21, v21, v32, v34
	v_div_fixup_f32 v7, v21, v7, v1
	v_div_scale_f32 v1, s[0:1], v6, v6, v25
	v_rcp_f32_e32 v21, v1
	s_nop 0
	v_fma_f32 v32, -v1, v21, 1.0
	v_fmac_f32_e32 v21, v32, v21
	v_div_scale_f32 v32, vcc, v25, v6, v25
	v_mul_f32_e32 v33, v32, v21
	v_fma_f32 v34, -v1, v33, v32
	v_fmac_f32_e32 v33, v34, v21
	v_fma_f32 v1, -v1, v33, v32
	v_div_fmas_f32 v1, v1, v21, v33
	v_div_fixup_f32 v6, v1, v6, v25
	v_mul_f32_e32 v1, 0xbfb8aa3b, v30
	v_exp_f32_e32 v21, v1
	v_pk_mul_f32 v[6:7], v[26:27], v[6:7]
	v_pk_add_f32 v[20:21], v[20:21], 1.0 op_sel_hi:[1,0]
	s_nop 0
	v_div_scale_f32 v1, s[0:1], v21, v21, v30
	v_rcp_f32_e32 v25, v1
	s_nop 0
	v_fma_f32 v26, -v1, v25, 1.0
	v_fmac_f32_e32 v25, v26, v25
	v_div_scale_f32 v26, vcc, v30, v21, v30
	v_mul_f32_e32 v27, v26, v25
	v_fma_f32 v32, -v1, v27, v26
	v_fmac_f32_e32 v27, v32, v25
	v_fma_f32 v1, -v1, v27, v26
	v_div_fmas_f32 v1, v1, v25, v27
	v_div_fixup_f32 v21, v1, v21, v30
	v_div_scale_f32 v1, s[0:1], v20, v20, v31
	v_rcp_f32_e32 v25, v1
	s_nop 0
	v_fma_f32 v26, -v1, v25, 1.0
	v_fmac_f32_e32 v25, v26, v25
	v_div_scale_f32 v26, vcc, v31, v20, v31
	v_mul_f32_e32 v27, v26, v25
	v_fma_f32 v30, -v1, v27, v26
	v_fmac_f32_e32 v27, v30, v25
	v_fma_f32 v1, -v1, v27, v26
	v_div_fmas_f32 v1, v1, v25, v27
	v_mov_b32_e32 v26, v8
	v_mov_b32_e32 v27, v10
	v_mov_b32_e32 v10, v9
	v_pk_fma_f32 v[4:5], v[42:43], v[26:27], v[4:5] op_sel_hi:[0,1,1]
	v_pk_fma_f32 v[2:3], v[42:43], v[10:11], v[2:3] op_sel_hi:[0,1,1]
	v_mov_b32_e32 v8, v12
	v_mov_b32_e32 v9, v14
	v_mov_b32_e32 v14, v13
	v_div_fixup_f32 v20, v1, v20, v31
	v_pk_fma_f32 v[4:5], v[0:1], v[8:9], v[4:5] op_sel_hi:[0,1,1]
	v_pk_fma_f32 v[0:1], v[0:1], v[14:15], v[2:3] op_sel_hi:[0,1,1]
	v_mov_b32_e32 v2, v16
	v_mov_b32_e32 v3, v18
	v_and_b32_e32 v12, 0xffff0000, v22
	v_pk_fma_f32 v[2:3], v[24:25], v[2:3], v[4:5] op_sel_hi:[0,1,1]
	v_lshlrev_b32_e32 v9, 16, v23
	v_lshlrev_b32_e32 v10, 16, v22
	v_mul_f32_e32 v5, 0xbfb8aa3b, v12
	v_mul_f32_e32 v4, 0xbfb8aa3b, v10
	v_exp_f32_e32 v8, v5
	v_mul_f32_e32 v5, 0xbfb8aa3b, v9
	v_exp_f32_e32 v4, v4
	v_exp_f32_e32 v5, v5
	v_mov_b32_e32 v18, v17
	v_pk_mul_f32 v[2:3], v[48:49], v[2:3] op_sel_hi:[0,1]
	v_and_b32_e32 v11, 0xffff0000, v23
	v_pk_add_f32 v[4:5], v[4:5], 1.0 op_sel_hi:[1,0]
	v_pk_fma_f32 v[0:1], v[24:25], v[18:19], v[0:1] op_sel_hi:[0,1,1]
	v_div_scale_f32 v13, s[0:1], v5, v5, v9
	v_rcp_f32_e32 v14, v13
	v_pk_mul_f32 v[0:1], v[48:49], v[0:1] op_sel_hi:[0,1]
	v_pk_mul_f32 v[20:21], v[28:29], v[20:21]
	v_fma_f32 v15, -v13, v14, 1.0
	v_fmac_f32_e32 v14, v15, v14
	v_div_scale_f32 v15, vcc, v9, v5, v9
	v_mul_f32_e32 v16, v15, v14
	v_fma_f32 v17, -v13, v16, v15
	v_fmac_f32_e32 v16, v17, v14
	v_fma_f32 v13, -v13, v16, v15
	v_div_fmas_f32 v13, v13, v14, v16
	v_div_fixup_f32 v5, v13, v5, v9
	v_div_scale_f32 v9, s[0:1], v4, v4, v10
	v_rcp_f32_e32 v13, v9
	s_nop 0
	v_fma_f32 v14, -v9, v13, 1.0
	v_fmac_f32_e32 v13, v14, v13
	v_div_scale_f32 v14, vcc, v10, v4, v10
	v_mul_f32_e32 v15, v14, v13
	v_fma_f32 v16, -v9, v15, v14
	v_fmac_f32_e32 v15, v16, v13
	v_fma_f32 v9, -v9, v15, v14
	v_div_fmas_f32 v9, v9, v13, v15
	v_div_fixup_f32 v4, v9, v4, v10
	v_pk_mul_f32 v[2:3], v[2:3], v[4:5]
	v_mul_f32_e32 v4, 0xbfb8aa3b, v11
	v_exp_f32_e32 v9, v4
	s_nop 0
	v_pk_add_f32 v[4:5], v[8:9], 1.0 op_sel_hi:[1,0]
	s_nop 0
	v_div_scale_f32 v8, s[0:1], v5, v5, v11
	v_rcp_f32_e32 v9, v8
	s_nop 0
	v_fma_f32 v10, -v8, v9, 1.0
	v_fmac_f32_e32 v9, v10, v9
	v_div_scale_f32 v10, vcc, v11, v5, v11
	v_mul_f32_e32 v13, v10, v9
	v_fma_f32 v14, -v8, v13, v10
	v_fmac_f32_e32 v13, v14, v9
	v_fma_f32 v8, -v8, v13, v10
	v_div_fmas_f32 v8, v8, v9, v13
	v_div_fixup_f32 v5, v8, v5, v11
	v_div_scale_f32 v8, s[0:1], v4, v4, v12
	v_rcp_f32_e32 v9, v8
	s_mov_b64 s[0:1], s[36:37]
	v_fma_f32 v10, -v8, v9, 1.0
	v_fmac_f32_e32 v9, v10, v9
	v_div_scale_f32 v10, vcc, v12, v4, v12
	v_mul_f32_e32 v11, v10, v9
	v_fma_f32 v13, -v8, v11, v10
	v_fmac_f32_e32 v11, v13, v9
	v_fma_f32 v8, -v8, v11, v10
	v_div_fmas_f32 v8, v8, v9, v11
	v_div_fixup_f32 v4, v8, v4, v12
	v_pk_mul_f32 v[0:1], v[0:1], v[4:5]
	v_bfe_u32 v10, v2, 16, 1
	v_bfe_u32 v4, v1, 16, 1
	v_bfe_u32 v5, v0, 16, 1
	v_add3_u32 v0, v0, v5, s15
	v_add3_u32 v1, v1, v4, s15
	v_bfe_u32 v4, v6, 16, 1
	v_bfe_u32 v5, v7, 16, 1
	v_bfe_u32 v11, v3, 16, 1
	v_bfe_u32 v8, v21, 16, 1
	v_bfe_u32 v9, v20, 16, 1
	v_add3_u32 v3, v3, v11, s15
	v_add3_u32 v2, v2, v10, s15
	v_add3_u32 v5, v7, v5, s15
	v_add3_u32 v4, v6, v4, s15
	v_add3_u32 v9, v20, v9, s15
	v_add3_u32 v8, v21, v8, s15
	v_lshrrev_b32_e32 v4, 16, v4
	v_lshrrev_b32_e32 v5, 16, v5
	v_lshrrev_b32_e32 v2, 16, v2
	v_lshrrev_b32_e32 v3, 16, v3
	v_and_or_b32 v3, v1, s14, v3
	v_and_or_b32 v2, v0, s14, v2
	v_and_or_b32 v1, v8, s14, v5
	v_and_or_b32 v0, v9, s14, v4
	global_store_dwordx4 v[90:91], v[0:3], off offset:1024
	s_branch .LBB0_826
